# stack of small de-serializations on top: batched LRU look-back loads, SB next-stage K/V prefetch, LRU scan and carry with batched LDS reads, branch-free fast path for the G1 bf16 epilogue
# speedup vs baseline: 1.0043x; 1.0043x over previous
; __device__ __forceinline__ bf16_t f2bf(float f) { return (bf16_t)(cvt_pk_bf16(f, 0.f) & 0xffffu); }
; __device__ __forceinline__ float bf2f(bf16_t b) { return __uint_as_float(((unsigned)b) << 16); }
; template <int APPLY>
; __device__ void lru_item(PP p, int l, int bb, int ck, int nb, unsigned epoch) {
;     ...
;   {
;     const bf16_t* wsrc = p->lruWT + (long)((l * 8 + nb) * 2) * 4096;
;     const int d = tid >> 3, c8 = (tid & 7) * 8;
;     *(uint4*)(wta + d * 72 + c8) = *(const uint4*)(wsrc + d * 64 + c8);
;     *(uint4*)(wtx + d * 72 + c8) = *(const uint4*)(wsrc + 4096 + d * 64 + c8);
;   }
;   __syncthreads();
;   {
;     const int ch = tid & 63, gch = nb * 64 + ch;
;     const float* cw = p->conv_w + (long)l * 4 * 512 + gch;
;     const float w0 = cw[0], w1 = cw[512], w2 = cw[1024], w3 = cw[1536], cb = p->conv_b[l * 512 + gch];
; #pragma unroll
;     for (int i = 0; i < 16; ++i) {
;       const int tok = (tid >> 6) + 8 * i;
;       const float v = cb + w0 * bf2f(cxs[(tok + 0) * 64 + ch]) + w1 * bf2f(cxs[(tok + 1) * 64 + ch]) +
;                       w2 * bf2f(cxs[(tok + 2) * 64 + ch]) + w3 * bf2f(cxs[(tok + 3) * 64 + ch]);
;       xcs[tok * 72 + ch] = f2bf(v);
;     }
;   }
.LBB0_122:
	s_or_b64 exec, exec, s[4:5]
	s_load_dwordx4 s[40:43], s[0:1], 0x110
	s_mov_b64 s[4:5], 0x1e00
	v_lshl_add_u64 v[22:23], v[6:7], 0, s[4:5]
	s_lshl_b32 s4, s6, 14
	s_or_b32 s4, s4, s74
	v_ashrrev_i32_e32 v4, 3, v24
	s_waitcnt lgkmcnt(0)
	s_add_u32 s4, s40, s4
	v_lshlrev_b32_e32 v2, 6, v4
	s_addc_u32 s5, s41, 0
	v_ashrrev_i32_e32 v3, 31, v2
	v_lshlrev_b32_e32 v0, 4, v24
	v_lshl_add_u64 v[2:3], v[2:3], 1, s[4:5]
	v_and_b32_e32 v0, 0x70, v0
	s_movk_i32 s8, 0x90
	v_lshl_add_u64 v[6:7], v[2:3], 0, v[0:1]
	v_mul_lo_u32 v2, v4, s8
	v_add3_u32 v0, 0, v2, v0
	global_load_dwordx4 v[120:123], v[6:7], off
	s_movk_i32 s4, 0x2000
	v_or_b32_e32 v8, s89, v71
	s_movk_i32 s6, 0x1000
	v_and_b32_e32 v30, 15, v24
	v_mov_b32_e32 v55, 0x3ecc95a3
	s_mov_b32 s13, 0x7f800000
	v_mov_b32_e32 v57, 0x7f800000
	v_mov_b32_e32 v73, 0x7fc00000
	v_mov_b32_e32 v74, 0xff800000
	s_mov_b32 s30, 0x33800000
	s_mov_b32 s31, 0xf800000
	v_mov_b32_e32 v56, 0x260
	v_add_co_u32_e32 v2, vcc, s4, v6
	s_nop 1
	v_addc_co_u32_e32 v3, vcc, 0, v7, vcc
	global_load_dwordx4 v[124:127], v[2:3], off
	s_waitcnt vmcnt(0)
	ds_write_b128 v112, v[100:103]
	ds_write_b128 v113, v[104:107]
	v_cmp_gt_i32_e32 vcc, 24, v24
	s_and_saveexec_b64 s[38:39], vcc
	ds_write_b128 v114, v[108:111]
	s_or_b64 exec, exec, s[38:39]
	ds_write_b128 v0, v[120:123] offset:35328
	ds_write_b128 v0, v[124:127] offset:44544
	s_waitcnt lgkmcnt(0)
	s_barrier
	s_load_dwordx4 s[44:47], s[0:1], 0x38
	s_load_dwordx2 s[56:57], s[0:1], 0x50
	s_load_dwordx2 s[48:49], s[0:1], 0x60
	s_load_dwordx2 s[50:51], s[0:1], 0xf8
	v_lshlrev_b32_e32 v0, 2, v8
	s_waitcnt lgkmcnt(0)
	s_add_u32 s40, s44, s78
	s_addc_u32 s41, s45, 0
	v_lshl_add_u64 v[2:3], s[40:41], 0, v[0:1]
	global_load_dword v7, v0, s[40:41]
	global_load_dword v5, v0, s[40:41] offset:2048
	v_add_co_u32_e32 v2, vcc, s6, v2
	v_or_b32_e32 v0, s60, v8
	s_nop 0
	v_addc_co_u32_e32 v3, vcc, 0, v3, vcc
	v_lshlrev_b32_e32 v0, 2, v0
	global_load_dword v6, v[2:3], off
	global_load_dword v4, v[2:3], off offset:2048
	global_load_dword v8, v0, s[46:47]
	v_lshlrev_b32_e32 v2, 1, v24
	v_add_u32_e32 v0, 0, v18
	v_and_b32_e32 v2, 0xffffff80, v2
	v_add_u32_e32 v3, v0, v2
	ds_read_u16 v3, v3
	v_add3_u32 v2, 0, v2, v18
	ds_read_u16 v9, v2 offset:128
	s_waitcnt lgkmcnt(1)
	v_lshlrev_b32_e32 v3, 16, v3
	s_waitcnt lgkmcnt(0)
	v_lshlrev_b32_e32 v9, 16, v9
	s_waitcnt vmcnt(0)
	v_fma_f32 v3, v7, v3, v8
	v_fmac_f32_e32 v3, v5, v9
	ds_read_u16 v9, v2 offset:256
	ds_read_u16 v2, v2 offset:384
	s_waitcnt lgkmcnt(1)
	v_lshlrev_b32_e32 v9, 16, v9
	v_fmac_f32_e32 v3, v6, v9
	s_waitcnt lgkmcnt(0)
	v_lshlrev_b32_e32 v2, 16, v2
	v_fmac_f32_e32 v3, v4, v2
	v_cvt_pk_bf16_f32 v9, v3, s0
	v_mad_u64_u32 v[2:3], s[4:5], v27, s8, v[0:1]
	v_lshlrev_b32_e32 v3, 7, v27
	ds_write_b16 v2, v9 offset:16896
	v_add_u32_e32 v9, 0x400, v3
	v_add_u32_e32 v10, v0, v9
	ds_read_u16 v10, v10
	v_add3_u32 v9, 0, v9, v18
	ds_read_u16 v11, v9 offset:128
	s_mov_b32 s5, 0x3f2aaaab
	s_movk_i32 s4, 0x300
	s_waitcnt lgkmcnt(1)
	v_lshlrev_b32_e32 v10, 16, v10
	v_fma_f32 v10, v7, v10, v8
	s_waitcnt lgkmcnt(0)
	v_lshlrev_b32_e32 v11, 16, v11
	v_fmac_f32_e32 v10, v5, v11
	ds_read_u16 v11, v9 offset:256
	ds_read_u16 v9, v9 offset:384
	s_waitcnt lgkmcnt(1)
	v_lshlrev_b32_e32 v11, 16, v11
	v_fmac_f32_e32 v10, v6, v11
	s_waitcnt lgkmcnt(0)
	v_lshlrev_b32_e32 v9, 16, v9
	v_fmac_f32_e32 v10, v4, v9
	v_cvt_pk_bf16_f32 v9, v10, s0
	ds_write_b16 v2, v9 offset:18048
	v_add_u32_e32 v9, 0x800, v3
	v_add_u32_e32 v10, v0, v9
	ds_read_u16 v10, v10
	v_add3_u32 v9, 0, v9, v18
	ds_read_u16 v11, v9 offset:128
	s_waitcnt lgkmcnt(1)
	v_lshlrev_b32_e32 v10, 16, v10
	v_fma_f32 v10, v7, v10, v8
	s_waitcnt lgkmcnt(0)
	v_lshlrev_b32_e32 v11, 16, v11
	v_fmac_f32_e32 v10, v5, v11
	ds_read_u16 v11, v9 offset:256
	ds_read_u16 v9, v9 offset:384
	s_waitcnt lgkmcnt(1)
	v_lshlrev_b32_e32 v11, 16, v11
	v_fmac_f32_e32 v10, v6, v11
	s_waitcnt lgkmcnt(0)
	v_lshlrev_b32_e32 v9, 16, v9
	v_fmac_f32_e32 v10, v4, v9
	v_cvt_pk_bf16_f32 v9, v10, s0
	ds_write_b16 v2, v9 offset:19200
	v_add_u32_e32 v9, 0xc00, v3
	v_add_u32_e32 v10, v0, v9
	ds_read_u16 v10, v10
	v_add3_u32 v9, 0, v9, v18
	ds_read_u16 v11, v9 offset:128
	s_waitcnt lgkmcnt(1)
	v_lshlrev_b32_e32 v10, 16, v10
	v_fma_f32 v10, v7, v10, v8
	s_waitcnt lgkmcnt(0)
	v_lshlrev_b32_e32 v11, 16, v11
	v_fmac_f32_e32 v10, v5, v11
	ds_read_u16 v11, v9 offset:256
	ds_read_u16 v9, v9 offset:384
	s_waitcnt lgkmcnt(1)
	v_lshlrev_b32_e32 v11, 16, v11
	v_fmac_f32_e32 v10, v6, v11
	s_waitcnt lgkmcnt(0)
	v_lshlrev_b32_e32 v9, 16, v9
	v_fmac_f32_e32 v10, v4, v9
	v_cvt_pk_bf16_f32 v9, v10, s0
	ds_write_b16 v2, v9 offset:20352
	v_add_u32_e32 v9, 0x1000, v3
	v_add_u32_e32 v10, v0, v9
	ds_read_u16 v10, v10
	v_add3_u32 v9, 0, v9, v18
	ds_read_u16 v11, v9 offset:128
	s_waitcnt lgkmcnt(1)
	v_lshlrev_b32_e32 v10, 16, v10
	v_fma_f32 v10, v7, v10, v8
	s_waitcnt lgkmcnt(0)
	v_lshlrev_b32_e32 v11, 16, v11
	v_fmac_f32_e32 v10, v5, v11
	ds_read_u16 v11, v9 offset:256
	ds_read_u16 v9, v9 offset:384
	s_waitcnt lgkmcnt(1)
	v_lshlrev_b32_e32 v11, 16, v11
	v_fmac_f32_e32 v10, v6, v11
	s_waitcnt lgkmcnt(0)
	v_lshlrev_b32_e32 v9, 16, v9
	v_fmac_f32_e32 v10, v4, v9
	v_cvt_pk_bf16_f32 v9, v10, s0
	ds_write_b16 v2, v9 offset:21504
	v_add_u32_e32 v9, 0x1400, v3
	v_add_u32_e32 v10, v0, v9
	ds_read_u16 v10, v10
	v_add3_u32 v9, 0, v9, v18
	ds_read_u16 v11, v9 offset:128
	s_waitcnt lgkmcnt(1)
	v_lshlrev_b32_e32 v10, 16, v10
	v_fma_f32 v10, v7, v10, v8
	s_waitcnt lgkmcnt(0)
	v_lshlrev_b32_e32 v11, 16, v11
	v_fmac_f32_e32 v10, v5, v11
	ds_read_u16 v11, v9 offset:256
	ds_read_u16 v9, v9 offset:384
	s_waitcnt lgkmcnt(1)
	v_lshlrev_b32_e32 v11, 16, v11
	v_fmac_f32_e32 v10, v6, v11
	s_waitcnt lgkmcnt(0)
; __device__ __forceinline__ bf16_t f2bf(float f) { return (bf16_t)(cvt_pk_bf16(f, 0.f) & 0xffffu); }
; __device__ __forceinline__ float bf2f(bf16_t b) { return __uint_as_float(((unsigned)b) << 16); }
; template <int APPLY>
; __device__ void lru_item(PP p, int l, int bb, int ck, int nb, unsigned epoch) {
;     ...
;   {
;     const int ch = tid & 63, gch = nb * 64 + ch;
;     const float* cw = p->conv_w + (long)l * 4 * 512 + gch;
;     const float w0 = cw[0], w1 = cw[512], w2 = cw[1024], w3 = cw[1536], cb = p->conv_b[l * 512 + gch];
; #pragma unroll
;     for (int i = 0; i < 16; ++i) {
;       const int tok = (tid >> 6) + 8 * i;
;       const float v = cb + w0 * bf2f(cxs[(tok + 0) * 64 + ch]) + w1 * bf2f(cxs[(tok + 1) * 64 + ch]) +
;                       w2 * bf2f(cxs[(tok + 2) * 64 + ch]) + w3 * bf2f(cxs[(tok + 3) * 64 + ch]);
;       xcs[tok * 72 + ch] = f2bf(v);
;     }
;   }
;   __syncthreads();
	v_lshlrev_b32_e32 v9, 16, v9
	v_fmac_f32_e32 v10, v4, v9
	v_cvt_pk_bf16_f32 v9, v10, s0
	ds_write_b16 v2, v9 offset:22656
	v_add_u32_e32 v9, 0x1800, v3
	v_add_u32_e32 v10, v0, v9
	ds_read_u16 v10, v10
	v_add3_u32 v9, 0, v9, v18
	ds_read_u16 v11, v9 offset:128
	s_waitcnt lgkmcnt(1)
	v_lshlrev_b32_e32 v10, 16, v10
	v_fma_f32 v10, v7, v10, v8
	s_waitcnt lgkmcnt(0)
	v_lshlrev_b32_e32 v11, 16, v11
	v_fmac_f32_e32 v10, v5, v11
	ds_read_u16 v11, v9 offset:256
	ds_read_u16 v9, v9 offset:384
	s_waitcnt lgkmcnt(1)
	v_lshlrev_b32_e32 v11, 16, v11
	v_fmac_f32_e32 v10, v6, v11
	s_waitcnt lgkmcnt(0)
	v_lshlrev_b32_e32 v9, 16, v9
	v_fmac_f32_e32 v10, v4, v9
	v_cvt_pk_bf16_f32 v9, v10, s0
	ds_write_b16 v2, v9 offset:23808
	v_add_u32_e32 v9, 0x1c00, v3
	v_add_u32_e32 v10, v0, v9
	ds_read_u16 v10, v10
	v_add3_u32 v9, 0, v9, v18
	ds_read_u16 v11, v9 offset:128
	s_waitcnt lgkmcnt(1)
	v_lshlrev_b32_e32 v10, 16, v10
	v_fma_f32 v10, v7, v10, v8
	s_waitcnt lgkmcnt(0)
	v_lshlrev_b32_e32 v11, 16, v11
	v_fmac_f32_e32 v10, v5, v11
	ds_read_u16 v11, v9 offset:256
	ds_read_u16 v9, v9 offset:384
	s_waitcnt lgkmcnt(1)
	v_lshlrev_b32_e32 v11, 16, v11
	v_fmac_f32_e32 v10, v6, v11
	s_waitcnt lgkmcnt(0)
	v_lshlrev_b32_e32 v9, 16, v9
	v_fmac_f32_e32 v10, v4, v9
	v_cvt_pk_bf16_f32 v9, v10, s0
	ds_write_b16 v2, v9 offset:24960
	v_add_u32_e32 v9, 0x2000, v3
	v_add_u32_e32 v10, v0, v9
	ds_read_u16 v10, v10
	v_add3_u32 v9, 0, v9, v18
	ds_read_u16 v11, v9 offset:128
	s_waitcnt lgkmcnt(1)
	v_lshlrev_b32_e32 v10, 16, v10
	v_fma_f32 v10, v7, v10, v8
	s_waitcnt lgkmcnt(0)
	v_lshlrev_b32_e32 v11, 16, v11
	v_fmac_f32_e32 v10, v5, v11
	ds_read_u16 v11, v9 offset:256
	ds_read_u16 v9, v9 offset:384
	s_waitcnt lgkmcnt(1)
	v_lshlrev_b32_e32 v11, 16, v11
	v_fmac_f32_e32 v10, v6, v11
	s_waitcnt lgkmcnt(0)
	v_lshlrev_b32_e32 v9, 16, v9
	v_fmac_f32_e32 v10, v4, v9
	v_cvt_pk_bf16_f32 v9, v10, s0
	ds_write_b16 v2, v9 offset:26112
	v_add_u32_e32 v9, 0x2400, v3
	v_add_u32_e32 v10, v0, v9
	ds_read_u16 v10, v10
	v_add3_u32 v9, 0, v9, v18
	ds_read_u16 v11, v9 offset:128
	s_waitcnt lgkmcnt(1)
	v_lshlrev_b32_e32 v10, 16, v10
	v_fma_f32 v10, v7, v10, v8
	s_waitcnt lgkmcnt(0)
	v_lshlrev_b32_e32 v11, 16, v11
	v_fmac_f32_e32 v10, v5, v11
	ds_read_u16 v11, v9 offset:256
	ds_read_u16 v9, v9 offset:384
	s_waitcnt lgkmcnt(1)
	v_lshlrev_b32_e32 v11, 16, v11
	v_fmac_f32_e32 v10, v6, v11
	s_waitcnt lgkmcnt(0)
	v_lshlrev_b32_e32 v9, 16, v9
	v_fmac_f32_e32 v10, v4, v9
	v_cvt_pk_bf16_f32 v9, v10, s0
	ds_write_b16 v2, v9 offset:27264
	v_add_u32_e32 v9, 0x2800, v3
	v_add_u32_e32 v10, v0, v9
	ds_read_u16 v10, v10
	v_add3_u32 v9, 0, v9, v18
	ds_read_u16 v11, v9 offset:128
	s_waitcnt lgkmcnt(1)
	v_lshlrev_b32_e32 v10, 16, v10
	v_fma_f32 v10, v7, v10, v8
	s_waitcnt lgkmcnt(0)
	v_lshlrev_b32_e32 v11, 16, v11
	v_fmac_f32_e32 v10, v5, v11
	ds_read_u16 v11, v9 offset:256
	ds_read_u16 v9, v9 offset:384
	s_waitcnt lgkmcnt(1)
	v_lshlrev_b32_e32 v11, 16, v11
	v_fmac_f32_e32 v10, v6, v11
	s_waitcnt lgkmcnt(0)
	v_lshlrev_b32_e32 v9, 16, v9
	v_fmac_f32_e32 v10, v4, v9
	v_cvt_pk_bf16_f32 v9, v10, s0
	ds_write_b16 v2, v9 offset:28416
	v_add_u32_e32 v9, 0x2c00, v3
	v_add_u32_e32 v10, v0, v9
	ds_read_u16 v10, v10
	v_add3_u32 v9, 0, v9, v18
	ds_read_u16 v11, v9 offset:128
	s_waitcnt lgkmcnt(1)
	v_lshlrev_b32_e32 v10, 16, v10
	v_fma_f32 v10, v7, v10, v8
	s_waitcnt lgkmcnt(0)
	v_lshlrev_b32_e32 v11, 16, v11
	v_fmac_f32_e32 v10, v5, v11
	ds_read_u16 v11, v9 offset:256
	ds_read_u16 v9, v9 offset:384
	s_waitcnt lgkmcnt(1)
	v_lshlrev_b32_e32 v11, 16, v11
	v_fmac_f32_e32 v10, v6, v11
	s_waitcnt lgkmcnt(0)
	v_lshlrev_b32_e32 v9, 16, v9
	v_fmac_f32_e32 v10, v4, v9
	v_cvt_pk_bf16_f32 v9, v10, s0
	ds_write_b16 v2, v9 offset:29568
	v_add_u32_e32 v9, 0x3000, v3
	v_add_u32_e32 v10, v0, v9
	ds_read_u16 v10, v10
	v_add3_u32 v9, 0, v9, v18
	ds_read_u16 v11, v9 offset:128
	s_waitcnt lgkmcnt(1)
	v_lshlrev_b32_e32 v10, 16, v10
	v_fma_f32 v10, v7, v10, v8
	s_waitcnt lgkmcnt(0)
	v_lshlrev_b32_e32 v11, 16, v11
	v_fmac_f32_e32 v10, v5, v11
	ds_read_u16 v11, v9 offset:256
	ds_read_u16 v9, v9 offset:384
	s_waitcnt lgkmcnt(1)
	v_lshlrev_b32_e32 v11, 16, v11
	v_fmac_f32_e32 v10, v6, v11
	s_waitcnt lgkmcnt(0)
	v_lshlrev_b32_e32 v9, 16, v9
	v_fmac_f32_e32 v10, v4, v9
	v_cvt_pk_bf16_f32 v9, v10, s0
	ds_write_b16 v2, v9 offset:30720
	v_add_u32_e32 v9, 0x3400, v3
	v_add_u32_e32 v10, v0, v9
	ds_read_u16 v10, v10
	v_add3_u32 v9, 0, v9, v18
	ds_read_u16 v11, v9 offset:128
	s_waitcnt lgkmcnt(1)
	v_lshlrev_b32_e32 v10, 16, v10
	v_fma_f32 v10, v7, v10, v8
	s_waitcnt lgkmcnt(0)
	v_lshlrev_b32_e32 v11, 16, v11
	v_fmac_f32_e32 v10, v5, v11
	ds_read_u16 v11, v9 offset:256
	ds_read_u16 v9, v9 offset:384
	s_waitcnt lgkmcnt(1)
	v_lshlrev_b32_e32 v11, 16, v11
	v_fmac_f32_e32 v10, v6, v11
	s_waitcnt lgkmcnt(0)
	v_lshlrev_b32_e32 v9, 16, v9
	v_fmac_f32_e32 v10, v4, v9
	v_cvt_pk_bf16_f32 v9, v10, s0
	ds_write_b16 v2, v9 offset:31872
	v_add_u32_e32 v9, 0x3800, v3
	v_add_u32_e32 v10, v0, v9
	ds_read_u16 v10, v10
	v_add3_u32 v9, 0, v9, v18
	ds_read_u16 v11, v9 offset:128
	v_add_u32_e32 v3, 0x3c00, v3
	v_add_u32_e32 v0, v0, v3
	s_waitcnt lgkmcnt(1)
	v_lshlrev_b32_e32 v10, 16, v10
	v_fma_f32 v10, v7, v10, v8
	s_waitcnt lgkmcnt(0)
	v_lshlrev_b32_e32 v11, 16, v11
	v_fmac_f32_e32 v10, v5, v11
	ds_read_u16 v11, v9 offset:256
	ds_read_u16 v9, v9 offset:384
	s_waitcnt lgkmcnt(1)
	v_lshlrev_b32_e32 v11, 16, v11
	v_fmac_f32_e32 v10, v6, v11
	s_waitcnt lgkmcnt(0)
	v_lshlrev_b32_e32 v9, 16, v9
	v_fmac_f32_e32 v10, v4, v9
	v_cvt_pk_bf16_f32 v9, v10, s0
	ds_write_b16 v2, v9 offset:33024
	ds_read_u16 v0, v0
	s_waitcnt lgkmcnt(0)
	v_lshlrev_b32_e32 v0, 16, v0
	v_fmac_f32_e32 v8, v7, v0
	v_add3_u32 v0, 0, v3, v18
	ds_read_u16 v3, v0 offset:128
	s_waitcnt lgkmcnt(0)
	v_lshlrev_b32_e32 v3, 16, v3
	v_fmac_f32_e32 v8, v5, v3
	ds_read_u16 v3, v0 offset:256
	ds_read_u16 v0, v0 offset:384
	s_waitcnt lgkmcnt(1)
	v_lshlrev_b32_e32 v3, 16, v3
	v_fmac_f32_e32 v8, v6, v3
	s_waitcnt lgkmcnt(0)
	v_lshlrev_b32_e32 v0, 16, v0
	v_fmac_f32_e32 v8, v4, v0
	v_cvt_pk_bf16_f32 v0, v8, s0
	ds_write_b16 v2, v0 offset:34176
	v_or_b32_e32 v0, v20, v30
	v_mul_lo_u32 v0, v0, s8
	v_and_b32_e32 v2, 48, v24
	v_add3_u32 v0, 0, v0, v2
	s_waitcnt lgkmcnt(0)
	s_barrier
; __device__ __forceinline__ float bf2f(bf16_t b) { return __uint_as_float(((unsigned)b) << 16); }
; __device__ __forceinline__ float sigmoidf_(float x) { return frcp(1.0f + fexp2(-x * LOG2E)); }
; template <int APPLY>
; __device__ void lru_item(PP p, int l, int bb, int ck, int nb, unsigned epoch) {
;     ...
;   {
;     bf16x8 a[2];
; #pragma unroll
;     for (int ks = 0; ks < 2; ++ks) a[ks] = *(const bf16x8*)(xcs + (wid * 16 + fr) * 72 + ks * 32 + fq * 8);
; #pragma unroll
;     for (int nk = 0; nk < 4; ++nk) {
;       f32x4 ra = f32x4{0.f, 0.f, 0.f, 0.f}, ia = f32x4{0.f, 0.f, 0.f, 0.f};
; #pragma unroll
;       for (int ks = 0; ks < 2; ++ks) {
;         bf16x8 ba = *(const bf16x8*)(wta + (nk * 16 + fr) * 72 + ks * 32 + fq * 8);
;         bf16x8 bx = *(const bf16x8*)(wtx + (nk * 16 + fr) * 72 + ks * 32 + fq * 8);
;         ra = __builtin_amdgcn_mfma_f32_16x16x32_bf16(a[ks], ba, ra, 0, 0, 0);
;         ia = __builtin_amdgcn_mfma_f32_16x16x32_bf16(a[ks], bx, ia, 0, 0, 0);
;       }
;       const int ch = nk * 16 + fr, gch = nb * 64 + ch;
;       const float ba_ = p->lru_b_a[l * 512 + gch], bx_ = p->lru_b_x[l * 512 + gch];
;       const float sp = log1pf(__expf(-p->lru_lambda[l * 512 + gch]));
;       const float* cw = p->conv_w + (long)l * 4 * 512 + gch;
;       const float w0 = cw[0], w1 = cw[512], w2 = cw[1024], w3 = cw[1536], cb = p->conv_b[l * 512 + gch];
; #pragma unroll
;       for (int reg = 0; reg < 4; ++reg) {
;         const int tok = wid * 16 + 4 * fq + reg;
;         const float r = sigmoidf_(ra[reg] + ba_), ig = sigmoidf_(ia[reg] + bx_);
;         const float log_a = -8.0f * r * sp;
;         const float av = __expf(log_a);
;         const float mult = sqrtf(fmaxf(1.0f - __expf(2.0f * log_a), 0.f));
;         const float xc = cb + w0 * bf2f(cxs[(tok + 0) * 64 + ch]) + w1 * bf2f(cxs[(tok + 1) * 64 + ch]) +
;                          w2 * bf2f(cxs[(tok + 2) * 64 + ch]) + w3 * bf2f(cxs[(tok + 3) * 64 + ch]);
;         as_[tok * 64 + ch] = av;
;         bs_[tok * 64 + ch] = mult * ig * xc;
;       }
	ds_read_b128 v[6:9], v0 offset:16896
	ds_read_b128 v[2:5], v0 offset:16960
	v_and_b32_e32 v0, 48, v71
	v_add_u32_e32 v34, 0, v0
	v_mul_u32_u24_e32 v0, 0x48, v30
	v_lshl_add_u32 v0, v0, 1, v34
	ds_read_b128 v[10:13], v0 offset:35328
	ds_read_b128 v[14:17], v0 offset:44544
	s_waitcnt lgkmcnt(0)
	v_mfma_f32_16x16x32_bf16 v[36:39], v[6:9], v[14:17], 0
	ds_read_b128 v[14:17], v0 offset:35392
	ds_read_b128 v[40:43], v0 offset:44608
	v_or_b32_e32 v0, s89, v30
	v_or_b32_e32 v25, s60, v0
	v_lshlrev_b32_e32 v25, 2, v25
	global_load_dword v29, v25, s[56:57]
	global_load_dword v28, v25, s[48:49]
	global_load_dword v26, v25, s[50:51]
	v_mfma_f32_16x16x32_bf16 v[10:13], v[6:9], v[10:13], 0
	s_mov_b32 s8, 0x3f317218
	v_lshlrev_b32_e32 v0, 2, v0
	s_waitcnt vmcnt(0)
	s_waitcnt lgkmcnt(1)
	v_mfma_f32_16x16x32_bf16 v[14:17], v[2:5], v[14:17], v[10:13]
	s_waitcnt lgkmcnt(0)
	v_mfma_f32_16x16x32_bf16 v[10:13], v[2:5], v[40:43], v[36:39]
	s_nop 5
	v_add_f32_e32 v14, v14, v29
	v_mul_f32_e32 v14, 0xbfb8aa3b, v14
	v_exp_f32_e32 v14, v14
	s_nop 4
	v_add_f32_e32 v10, v10, v28
	v_lshl_add_u64 v[36:37], s[40:41], 0, v[0:1]
	global_load_dword v39, v0, s[40:41]
	global_load_dword v40, v0, s[40:41] offset:2048
	v_add_f32_e32 v14, 1.0, v14
	v_rcp_f32_e32 v14, v14
	v_mul_f32_e32 v10, 0xbfb8aa3b, v10
	v_mul_f32_e32 v14, 0xc1000000, v14
	v_mov_b32_e32 v33, v26
	v_add_co_u32_e32 v36, vcc, s6, v36
	v_exp_f32_e32 v10, v10
	s_nop 0
	v_addc_co_u32_e32 v37, vcc, 0, v37, vcc
	global_load_dword v42, v[36:37], off
	global_load_dword v41, v[36:37], off offset:2048
	global_load_dword v0, v25, s[46:47]
	v_mul_f32_e32 v25, v14, v33
	v_mul_f32_e32 v14, 0x3fb8aa3b, v25
	v_add_f32_e32 v25, v25, v25
	v_mul_f32_e32 v25, 0x3fb8aa3b, v25
	v_exp_f32_e32 v25, v25
	v_add_f32_e32 v10, 1.0, v10
	v_rcp_f32_e32 v10, v10
	v_exp_f32_e32 v14, v14
	v_sub_f32_e32 v25, 1.0, v25
	v_max_f32_e32 v25, 0, v25
	v_cmp_gt_f32_e32 vcc, s31, v25
	v_mul_f32_e32 v26, 0x4f800000, v25
	v_add_f32_e32 v11, v11, v28
	v_cndmask_b32_e32 v25, v25, v26, vcc
	v_sqrt_f32_e32 v26, v25
	v_mul_f32_e32 v11, 0xbfb8aa3b, v11
	v_exp_f32_e32 v11, v11
	v_add_u32_e32 v31, -1, v26
	v_fma_f32 v32, -v31, v26, v25
	v_cmp_ge_f32_e64 s[38:39], 0, v32
	v_add_u32_e32 v32, 1, v26
	v_add_f32_e32 v11, 1.0, v11
	v_cndmask_b32_e64 v31, v26, v31, s[38:39]
	v_fma_f32 v26, -v32, v26, v25
	v_cmp_lt_f32_e64 s[38:39], 0, v26
	v_rcp_f32_e32 v11, v11
	s_nop 0
	v_cndmask_b32_e64 v26, v31, v32, s[38:39]
	v_mul_f32_e32 v31, 0x37800000, v26
	v_cndmask_b32_e32 v26, v26, v31, vcc
	v_cmp_class_f32_e32 vcc, v25, v56
	s_nop 1
	v_cndmask_b32_e32 v32, v26, v25, vcc
	v_lshlrev_b32_e32 v26, 4, v71
	v_lshlrev_b32_e32 v25, 10, v27
	v_and_or_b32 v38, v26, s4, v25
	v_or_b32_e32 v36, v38, v30
	v_lshlrev_b32_e32 v37, 1, v36
	v_add_u32_e32 v43, 0, v37
	ds_read_u16 v31, v43
	v_lshl_add_u32 v35, v38, 1, 0
	v_add_u32_e32 v37, v43, v37
	ds_write_b32 v37, v14 offset:53760
	v_mul_f32_e32 v10, v10, v32
	s_waitcnt lgkmcnt(1)
	v_lshlrev_b32_e32 v31, 16, v31
	v_lshlrev_b32_e32 v14, 2, v36
	v_readlane_b32 s4, v255, 45
	s_waitcnt vmcnt(0)
	v_fma_f32 v44, v39, v31, v0
	v_lshl_add_u32 v31, v30, 1, v35
	ds_read_u16 v45, v31 offset:128
	ds_read_u16 v46, v31 offset:256
	ds_read_u16 v47, v31 offset:384
	v_add_u32_e32 v32, s4, v14
	s_waitcnt lgkmcnt(2)
	v_lshlrev_b32_e32 v45, 16, v45
	v_fmac_f32_e32 v44, v40, v45
	s_waitcnt lgkmcnt(1)
	v_lshlrev_b32_e32 v46, 16, v46
	v_fmac_f32_e32 v44, v42, v46
	s_waitcnt lgkmcnt(0)
	v_lshlrev_b32_e32 v47, 16, v47
	v_fmac_f32_e32 v44, v41, v47
	v_mul_f32_e32 v10, v44, v10
	ds_write_b32 v32, v10
	v_add_f32_e32 v10, v15, v29
	v_mul_f32_e32 v10, 0xbfb8aa3b, v10
	v_exp_f32_e32 v10, v10
	v_fma_f32 v43, v39, v45, v0
	v_fmac_f32_e32 v43, v40, v46
	v_fmac_f32_e32 v43, v42, v47
	v_add_f32_e32 v10, 1.0, v10
	v_rcp_f32_e32 v10, v10
	s_nop 0
	v_mul_f32_e32 v10, 0xc1000000, v10
	v_mul_f32_e32 v10, v10, v33
	v_mul_f32_e32 v15, 0x3fb8aa3b, v10
	v_add_f32_e32 v10, v10, v10
	v_mul_f32_e32 v10, 0x3fb8aa3b, v10
	v_exp_f32_e32 v10, v10
	v_exp_f32_e32 v15, v15
	v_sub_f32_e32 v10, 1.0, v10
	v_max_f32_e32 v10, 0, v10
	v_cmp_gt_f32_e32 vcc, s31, v10
	v_mul_f32_e32 v32, 0x4f800000, v10
	s_nop 0
	v_cndmask_b32_e32 v10, v10, v32, vcc
	v_sqrt_f32_e32 v32, v10
	s_nop 0
	v_add_u32_e32 v36, -1, v32
	v_fma_f32 v37, -v36, v32, v10
	v_cmp_ge_f32_e64 s[38:39], 0, v37
	v_add_u32_e32 v37, 1, v32
	s_nop 0
	v_cndmask_b32_e64 v36, v32, v36, s[38:39]
	v_fma_f32 v32, -v37, v32, v10
	v_cmp_lt_f32_e64 s[38:39], 0, v32
	s_nop 1
	v_cndmask_b32_e64 v32, v36, v37, s[38:39]
	ds_read_u16 v37, v31 offset:512
	v_mul_f32_e32 v36, 0x37800000, v32
	v_cndmask_b32_e32 v32, v32, v36, vcc
	v_cmp_class_f32_e32 vcc, v10, v56
	v_or_b32_e32 v36, 64, v38
	s_waitcnt lgkmcnt(0)
	v_lshlrev_b32_e32 v44, 16, v37
	v_cndmask_b32_e32 v10, v32, v10, vcc
	v_or_b32_e32 v32, v36, v30
	v_fmac_f32_e32 v43, v41, v44
	v_mul_f32_e32 v10, v11, v10
	v_add_u32_e32 v37, 0, v14
	v_mul_f32_e32 v10, v43, v10
	v_lshl_add_u32 v11, v32, 2, s4
	ds_write_b32 v37, v15 offset:54016
	ds_write_b32 v11, v10
	v_add_f32_e32 v10, v16, v29
	v_mul_f32_e32 v10, 0xbfb8aa3b, v10
	v_exp_f32_e32 v10, v10
	v_add_f32_e32 v11, v12, v28
	v_mul_f32_e32 v11, 0xbfb8aa3b, v11
	v_exp_f32_e32 v11, v11
	v_add_f32_e32 v10, 1.0, v10
	v_rcp_f32_e32 v10, v10
	v_or_b32_e32 v32, 0x80, v38
	v_add_f32_e32 v11, 1.0, v11
	v_rcp_f32_e32 v11, v11
	v_mul_f32_e32 v10, 0xc1000000, v10
	v_mul_f32_e32 v10, v10, v33
	v_mul_f32_e32 v12, 0x3fb8aa3b, v10
	v_add_f32_e32 v10, v10, v10
	v_mul_f32_e32 v10, 0x3fb8aa3b, v10
	v_exp_f32_e32 v10, v10
	v_exp_f32_e32 v12, v12
	v_sub_f32_e32 v10, 1.0, v10
	v_max_f32_e32 v10, 0, v10
	v_cmp_gt_f32_e32 vcc, s31, v10
	v_mul_f32_e32 v14, 0x4f800000, v10
	ds_write_b32 v37, v12 offset:54272
	v_cndmask_b32_e32 v10, v10, v14, vcc
	v_sqrt_f32_e32 v14, v10
	s_nop 0
	v_add_u32_e32 v15, -1, v14
	v_fma_f32 v16, -v15, v14, v10
	v_cmp_ge_f32_e64 s[38:39], 0, v16
	v_add_u32_e32 v16, 1, v14
	s_nop 0
	v_cndmask_b32_e64 v15, v14, v15, s[38:39]
	v_fma_f32 v14, -v16, v14, v10
	v_cmp_lt_f32_e64 s[38:39], 0, v14
	s_nop 1
	v_cndmask_b32_e64 v14, v15, v16, s[38:39]
	ds_read_u16 v16, v31 offset:640
	v_mul_f32_e32 v15, 0x37800000, v14
	v_cndmask_b32_e32 v14, v14, v15, vcc
	v_fma_f32 v15, v39, v46, v0
	v_cmp_class_f32_e32 vcc, v10, v56
	v_fmac_f32_e32 v15, v40, v47
	v_fmac_f32_e32 v15, v42, v44
	v_cndmask_b32_e32 v10, v14, v10, vcc
	s_waitcnt lgkmcnt(0)
; __device__ __forceinline__ float bf2f(bf16_t b) { return __uint_as_float(((unsigned)b) << 16); }
; __device__ __forceinline__ float sigmoidf_(float x) { return frcp(1.0f + fexp2(-x * LOG2E)); }
; template <int APPLY>
; __device__ void lru_item(PP p, int l, int bb, int ck, int nb, unsigned epoch) {
;     ...
;       const int ch = nk * 16 + fr, gch = nb * 64 + ch;
;       const float ba_ = p->lru_b_a[l * 512 + gch], bx_ = p->lru_b_x[l * 512 + gch];
;       const float sp = log1pf(__expf(-p->lru_lambda[l * 512 + gch]));
;       const float* cw = p->conv_w + (long)l * 4 * 512 + gch;
;       const float w0 = cw[0], w1 = cw[512], w2 = cw[1024], w3 = cw[1536], cb = p->conv_b[l * 512 + gch];
; #pragma unroll
;       for (int reg = 0; reg < 4; ++reg) {
;         const int tok = wid * 16 + 4 * fq + reg;
;         const float r = sigmoidf_(ra[reg] + ba_), ig = sigmoidf_(ia[reg] + bx_);
;         const float log_a = -8.0f * r * sp;
;         const float av = __expf(log_a);
;         const float mult = sqrtf(fmaxf(1.0f - __expf(2.0f * log_a), 0.f));
;         const float xc = cb + w0 * bf2f(cxs[(tok + 0) * 64 + ch]) + w1 * bf2f(cxs[(tok + 1) * 64 + ch]) +
;                          w2 * bf2f(cxs[(tok + 2) * 64 + ch]) + w3 * bf2f(cxs[(tok + 3) * 64 + ch]);
;         as_[tok * 64 + ch] = av;
;         bs_[tok * 64 + ch] = mult * ig * xc;
;       }
	v_lshlrev_b32_e32 v16, 16, v16
	v_or_b32_e32 v14, v32, v30
	v_fmac_f32_e32 v15, v41, v16
	v_mul_f32_e32 v10, v11, v10
	v_mul_f32_e32 v10, v15, v10
	v_lshl_add_u32 v11, v14, 2, s4
	ds_write_b32 v11, v10
	v_add_f32_e32 v10, v17, v29
	v_mul_f32_e32 v10, 0xbfb8aa3b, v10
	v_exp_f32_e32 v10, v10
	v_add_f32_e32 v11, v13, v28
	v_mul_f32_e32 v11, 0xbfb8aa3b, v11
	v_exp_f32_e32 v11, v11
	v_add_f32_e32 v10, 1.0, v10
	v_rcp_f32_e32 v10, v10
	v_add_f32_e32 v11, 1.0, v11
	v_rcp_f32_e32 v11, v11
	v_mul_f32_e32 v10, 0xc1000000, v10
	v_mul_f32_e32 v10, v10, v33
	v_mul_f32_e32 v12, 0x3fb8aa3b, v10
	v_add_f32_e32 v10, v10, v10
	v_mul_f32_e32 v10, 0x3fb8aa3b, v10
	v_exp_f32_e32 v10, v10
	v_exp_f32_e32 v12, v12
	v_or_b32_e32 v33, 0xc0, v38
	v_sub_f32_e32 v10, 1.0, v10
	v_max_f32_e32 v10, 0, v10
	v_cmp_gt_f32_e32 vcc, s31, v10
	v_mul_f32_e32 v13, 0x4f800000, v10
	ds_write_b32 v37, v12 offset:54528
	v_cndmask_b32_e32 v10, v10, v13, vcc
	v_sqrt_f32_e32 v13, v10
	s_nop 0
	v_add_u32_e32 v14, -1, v13
	v_fma_f32 v15, -v14, v13, v10
	v_cmp_ge_f32_e64 s[38:39], 0, v15
	v_add_u32_e32 v15, 1, v13
	s_nop 0
	v_cndmask_b32_e64 v14, v13, v14, s[38:39]
	v_fma_f32 v13, -v15, v13, v10
	v_cmp_lt_f32_e64 s[38:39], 0, v13
	s_nop 1
	v_cndmask_b32_e64 v13, v14, v15, s[38:39]
	v_mul_f32_e32 v14, 0x37800000, v13
	v_cndmask_b32_e32 v13, v13, v14, vcc
	ds_read_u16 v14, v31 offset:384
	v_cmp_class_f32_e32 vcc, v10, v56
	s_waitcnt lgkmcnt(0)
	v_lshlrev_b32_e32 v14, 16, v14
	v_fmac_f32_e32 v0, v39, v14
	ds_read_u16 v14, v31 offset:768
	v_fmac_f32_e32 v0, v40, v44
	v_cndmask_b32_e32 v10, v13, v10, vcc
	v_fmac_f32_e32 v0, v42, v16
	v_or_b32_e32 v13, v33, v30
	s_waitcnt lgkmcnt(0)
	v_lshlrev_b32_e32 v14, 16, v14
	v_fmac_f32_e32 v0, v41, v14
	v_mul_f32_e32 v10, v11, v10
	v_mul_f32_e32 v0, v0, v10
	v_lshl_add_u32 v10, v13, 2, s4
	v_or_b32_e32 v40, 16, v30
	ds_write_b32 v10, v0
	v_mul_u32_u24_e32 v0, 0x48, v40
	v_lshl_add_u32 v0, v0, 1, v34
	ds_read_b128 v[10:13], v0 offset:35328
	ds_read_b128 v[14:17], v0 offset:44544
	s_waitcnt lgkmcnt(0)
	v_mfma_f32_16x16x32_bf16 v[42:45], v[6:9], v[14:17], 0
	ds_read_b128 v[14:17], v0 offset:35392
	ds_read_b128 v[46:49], v0 offset:44608
	v_add_u32_e32 v0, s89, v30
	v_add_lshl_u32 v39, v0, s60, 2
	v_mfma_f32_16x16x32_bf16 v[10:13], v[6:9], v[10:13], 0
	v_lshlrev_b32_e32 v0, 2, v0
	s_waitcnt lgkmcnt(1)
	v_mfma_f32_16x16x32_bf16 v[14:17], v[2:5], v[14:17], v[10:13]
	s_waitcnt lgkmcnt(0)
	v_mfma_f32_16x16x32_bf16 v[10:13], v[2:5], v[46:49], v[42:45]
	s_nop 2
	global_load_dword v42, v39, s[56:57] offset:64
	global_load_dword v41, v39, s[48:49] offset:64
	global_load_dword v28, v39, s[50:51] offset:64
	s_waitcnt vmcnt(2)
	v_add_f32_e32 v14, v14, v42
	v_mul_f32_e32 v14, 0xbfb8aa3b, v14
	s_waitcnt vmcnt(0)
	v_exp_f32_e32 v14, v14
	v_add_f32_e32 v10, v10, v41
	v_mul_f32_e32 v10, 0xbfb8aa3b, v10
	v_add_f32_e32 v14, 1.0, v14
	global_load_dword v44, v0, s[40:41] offset:64
	global_load_dword v45, v0, s[40:41] offset:2112
	v_rcp_f32_e32 v14, v14
	v_exp_f32_e32 v10, v10
	v_mul_f32_e32 v14, 0xc1000000, v14
	v_add_f32_e32 v10, 1.0, v10
	v_mov_b32_e32 v48, v28
	v_lshl_add_u64 v[28:29], s[40:41], 0, v[0:1]
	v_add_co_u32_e32 v28, vcc, s6, v28
	v_mul_f32_e32 v49, v14, v48
	s_nop 0
	v_addc_co_u32_e32 v29, vcc, 0, v29, vcc
	global_load_dword v47, v[28:29], off offset:64
	global_load_dword v46, v[28:29], off offset:2112
	global_load_dword v43, v39, s[46:47] offset:64
	v_mul_f32_e32 v14, 0x3fb8aa3b, v49
	v_add_f32_e32 v49, v49, v49
	v_mul_f32_e32 v49, 0x3fb8aa3b, v49
	v_exp_f32_e32 v49, v49
	ds_read_u16 v53, v31 offset:288
	ds_read_u16 v54, v31 offset:416
	v_rcp_f32_e32 v10, v10
	v_sub_f32_e32 v49, 1.0, v49
	v_max_f32_e32 v49, 0, v49
	v_cmp_gt_f32_e32 vcc, s31, v49
	v_mul_f32_e32 v50, 0x4f800000, v49
	v_exp_f32_e32 v14, v14
	v_cndmask_b32_e32 v49, v49, v50, vcc
	v_sqrt_f32_e32 v50, v49
	s_waitcnt lgkmcnt(1)
	v_lshlrev_b32_e32 v53, 16, v53
	s_waitcnt lgkmcnt(0)
	v_lshlrev_b32_e32 v54, 16, v54
	ds_write_b32 v37, v14 offset:53824
	v_add_u32_e32 v51, -1, v50
	v_fma_f32 v52, -v51, v50, v49
	v_cmp_ge_f32_e64 s[38:39], 0, v52
	v_add_u32_e32 v52, 1, v50
	v_add_f32_e32 v11, v11, v41
	v_cndmask_b32_e64 v51, v50, v51, s[38:39]
	v_fma_f32 v50, -v52, v50, v49
	v_cmp_lt_f32_e64 s[38:39], 0, v50
	v_mul_f32_e32 v11, 0xbfb8aa3b, v11
	v_exp_f32_e32 v11, v11
	v_cndmask_b32_e64 v50, v51, v52, s[38:39]
	v_mul_f32_e32 v51, 0x37800000, v50
	v_cndmask_b32_e32 v50, v50, v51, vcc
	ds_read_u16 v51, v31 offset:32
	ds_read_u16 v52, v31 offset:160
	v_cmp_class_f32_e32 vcc, v49, v56
	v_add_f32_e32 v11, 1.0, v11
	v_rcp_f32_e32 v11, v11
	s_waitcnt lgkmcnt(1)
	v_lshlrev_b32_e32 v51, 16, v51
	s_waitcnt lgkmcnt(0)
	v_lshlrev_b32_e32 v52, 16, v52
	v_cndmask_b32_e32 v50, v50, v49, vcc
	v_or_b32_e32 v49, v38, v40
	v_mul_f32_e32 v10, v10, v50
	v_lshlrev_b32_e32 v14, 2, v49
	v_add_u32_e32 v49, s4, v14
	v_add_u32_e32 v14, 0, v14
	s_waitcnt vmcnt(0)
	v_fma_f32 v51, v44, v51, v43
	v_fmac_f32_e32 v51, v45, v52
	v_fmac_f32_e32 v51, v47, v53
	v_fmac_f32_e32 v51, v46, v54
	v_mul_f32_e32 v10, v51, v10
	ds_write_b32 v49, v10
	v_add_f32_e32 v10, v15, v42
	v_mul_f32_e32 v10, 0xbfb8aa3b, v10
	v_exp_f32_e32 v10, v10
	s_nop 0
	v_add_f32_e32 v10, 1.0, v10
	v_rcp_f32_e32 v10, v10
	s_nop 0
	v_mul_f32_e32 v10, 0xc1000000, v10
	v_mul_f32_e32 v10, v10, v48
	v_mul_f32_e32 v15, 0x3fb8aa3b, v10
	v_add_f32_e32 v10, v10, v10
	v_mul_f32_e32 v10, 0x3fb8aa3b, v10
	v_exp_f32_e32 v10, v10
	v_exp_f32_e32 v15, v15
	v_sub_f32_e32 v10, 1.0, v10
	v_max_f32_e32 v10, 0, v10
	v_cmp_gt_f32_e32 vcc, s31, v10
	v_mul_f32_e32 v49, 0x4f800000, v10
	ds_write_b32 v14, v15 offset:54016
	v_cndmask_b32_e32 v10, v10, v49, vcc
	v_sqrt_f32_e32 v49, v10
	s_nop 0
	v_add_u32_e32 v50, -1, v49
	v_fma_f32 v51, -v50, v49, v10
	v_cmp_ge_f32_e64 s[38:39], 0, v51
	v_add_u32_e32 v51, 1, v49
	s_nop 0
	v_cndmask_b32_e64 v50, v49, v50, s[38:39]
	v_fma_f32 v49, -v51, v49, v10
	v_cmp_lt_f32_e64 s[38:39], 0, v49
	s_nop 1
	v_cndmask_b32_e64 v49, v50, v51, s[38:39]
	v_fma_f32 v51, v44, v52, v43
	ds_read_u16 v52, v31 offset:544
	v_mul_f32_e32 v50, 0x37800000, v49
	v_cndmask_b32_e32 v49, v49, v50, vcc
	v_cmp_class_f32_e32 vcc, v10, v56
	v_fmac_f32_e32 v51, v45, v53
	v_fmac_f32_e32 v51, v47, v54
	v_cndmask_b32_e32 v10, v49, v10, vcc
	s_waitcnt lgkmcnt(0)
; __device__ __forceinline__ float bf2f(bf16_t b) { return __uint_as_float(((unsigned)b) << 16); }
; __device__ __forceinline__ float sigmoidf_(float x) { return frcp(1.0f + fexp2(-x * LOG2E)); }
; template <int APPLY>
; __device__ void lru_item(PP p, int l, int bb, int ck, int nb, unsigned epoch) {
;     ...
;       const int ch = nk * 16 + fr, gch = nb * 64 + ch;
;       const float ba_ = p->lru_b_a[l * 512 + gch], bx_ = p->lru_b_x[l * 512 + gch];
;       const float sp = log1pf(__expf(-p->lru_lambda[l * 512 + gch]));
;       const float* cw = p->conv_w + (long)l * 4 * 512 + gch;
;       const float w0 = cw[0], w1 = cw[512], w2 = cw[1024], w3 = cw[1536], cb = p->conv_b[l * 512 + gch];
; #pragma unroll
;       for (int reg = 0; reg < 4; ++reg) {
;         const int tok = wid * 16 + 4 * fq + reg;
;         const float r = sigmoidf_(ra[reg] + ba_), ig = sigmoidf_(ia[reg] + bx_);
;         const float log_a = -8.0f * r * sp;
;         const float av = __expf(log_a);
;         const float mult = sqrtf(fmaxf(1.0f - __expf(2.0f * log_a), 0.f));
;         const float xc = cb + w0 * bf2f(cxs[(tok + 0) * 64 + ch]) + w1 * bf2f(cxs[(tok + 1) * 64 + ch]) +
;                          w2 * bf2f(cxs[(tok + 2) * 64 + ch]) + w3 * bf2f(cxs[(tok + 3) * 64 + ch]);
;         as_[tok * 64 + ch] = av;
;         bs_[tok * 64 + ch] = mult * ig * xc;
;       }
	v_lshlrev_b32_e32 v52, 16, v52
	v_or_b32_e32 v49, v36, v40
	v_fmac_f32_e32 v51, v46, v52
	v_mul_f32_e32 v10, v11, v10
	v_mul_f32_e32 v10, v51, v10
	v_lshl_add_u32 v11, v49, 2, s4
	ds_write_b32 v11, v10
	v_add_f32_e32 v10, v16, v42
	v_mul_f32_e32 v10, 0xbfb8aa3b, v10
	v_exp_f32_e32 v10, v10
	v_add_f32_e32 v11, v12, v41
	v_mul_f32_e32 v11, 0xbfb8aa3b, v11
	v_exp_f32_e32 v11, v11
	v_add_f32_e32 v10, 1.0, v10
	v_rcp_f32_e32 v10, v10
	v_lshl_add_u32 v50, v40, 1, v35
	v_add_f32_e32 v11, 1.0, v11
	v_rcp_f32_e32 v11, v11
	v_mul_f32_e32 v10, 0xc1000000, v10
	v_mul_f32_e32 v10, v10, v48
	v_mul_f32_e32 v12, 0x3fb8aa3b, v10
	v_add_f32_e32 v10, v10, v10
	v_mul_f32_e32 v10, 0x3fb8aa3b, v10
	v_exp_f32_e32 v10, v10
	v_exp_f32_e32 v12, v12
	v_sub_f32_e32 v10, 1.0, v10
	v_max_f32_e32 v10, 0, v10
	v_cmp_gt_f32_e32 vcc, s31, v10
	v_mul_f32_e32 v15, 0x4f800000, v10
	ds_write_b32 v14, v12 offset:54272
	v_cndmask_b32_e32 v10, v10, v15, vcc
	v_sqrt_f32_e32 v15, v10
	s_nop 0
	v_add_u32_e32 v16, -1, v15
	v_fma_f32 v49, -v16, v15, v10
	v_cmp_ge_f32_e64 s[38:39], 0, v49
	v_add_u32_e32 v49, 1, v15
	s_nop 0
	v_cndmask_b32_e64 v16, v15, v16, s[38:39]
	v_fma_f32 v15, -v49, v15, v10
	v_cmp_lt_f32_e64 s[38:39], 0, v15
	s_nop 1
	v_cndmask_b32_e64 v15, v16, v49, s[38:39]
	ds_read_u16 v49, v31 offset:672
	v_mul_f32_e32 v16, 0x37800000, v15
	v_cndmask_b32_e32 v15, v15, v16, vcc
	v_fma_f32 v16, v44, v53, v43
	v_cmp_class_f32_e32 vcc, v10, v56
	v_fmac_f32_e32 v16, v45, v54
	v_fmac_f32_e32 v16, v47, v52
	v_cndmask_b32_e32 v10, v15, v10, vcc
	s_waitcnt lgkmcnt(0)
	v_lshlrev_b32_e32 v49, 16, v49
	v_or_b32_e32 v15, v32, v40
	v_fmac_f32_e32 v16, v46, v49
	v_mul_f32_e32 v10, v11, v10
	v_mul_f32_e32 v10, v16, v10
	v_lshl_add_u32 v11, v15, 2, s4
	ds_write_b32 v11, v10
	v_add_f32_e32 v10, v17, v42
	v_mul_f32_e32 v10, 0xbfb8aa3b, v10
	v_exp_f32_e32 v10, v10
	v_add_f32_e32 v11, v13, v41
	v_mul_f32_e32 v11, 0xbfb8aa3b, v11
	v_exp_f32_e32 v11, v11
	v_add_f32_e32 v10, 1.0, v10
	v_rcp_f32_e32 v10, v10
	v_add_f32_e32 v11, 1.0, v11
	v_rcp_f32_e32 v11, v11
	v_mul_f32_e32 v10, 0xc1000000, v10
	v_mul_f32_e32 v10, v10, v48
	v_mul_f32_e32 v12, 0x3fb8aa3b, v10
	v_add_f32_e32 v10, v10, v10
	v_mul_f32_e32 v10, 0x3fb8aa3b, v10
	v_exp_f32_e32 v10, v10
	v_exp_f32_e32 v12, v12
	v_sub_f32_e32 v10, 1.0, v10
	v_max_f32_e32 v10, 0, v10
	v_cmp_gt_f32_e32 vcc, s31, v10
	v_mul_f32_e32 v13, 0x4f800000, v10
	ds_write_b32 v14, v12 offset:54528
	v_cndmask_b32_e32 v10, v10, v13, vcc
	v_sqrt_f32_e32 v13, v10
	s_nop 0
	v_add_u32_e32 v15, -1, v13
	v_fma_f32 v16, -v15, v13, v10
	v_cmp_ge_f32_e64 s[38:39], 0, v16
	v_add_u32_e32 v16, 1, v13
	s_nop 0
	v_cndmask_b32_e64 v15, v13, v15, s[38:39]
	v_fma_f32 v13, -v16, v13, v10
	v_cmp_lt_f32_e64 s[38:39], 0, v13
	s_nop 1
	v_cndmask_b32_e64 v13, v15, v16, s[38:39]
	v_mul_f32_e32 v15, 0x37800000, v13
	v_cndmask_b32_e32 v13, v13, v15, vcc
	ds_read_u16 v15, v50 offset:384
	v_cmp_class_f32_e32 vcc, v10, v56
	s_waitcnt lgkmcnt(0)
	v_lshlrev_b32_e32 v15, 16, v15
	v_fmac_f32_e32 v43, v44, v15
	ds_read_u16 v15, v31 offset:800
	v_fmac_f32_e32 v43, v45, v52
	v_cndmask_b32_e32 v10, v13, v10, vcc
	v_fmac_f32_e32 v43, v47, v49
	v_or_b32_e32 v13, v33, v40
	s_waitcnt lgkmcnt(0)
	v_lshlrev_b32_e32 v15, 16, v15
	v_fmac_f32_e32 v43, v46, v15
	v_mul_f32_e32 v10, v11, v10
	v_mul_f32_e32 v10, v43, v10
	v_lshl_add_u32 v11, v13, 2, s4
	v_or_b32_e32 v40, 32, v30
	ds_write_b32 v11, v10
	v_mul_u32_u24_e32 v10, 0x48, v40
	v_lshl_add_u32 v41, v10, 1, v34
	ds_read_b128 v[10:13], v41 offset:35328
	ds_read_b128 v[14:17], v41 offset:44544
	s_waitcnt lgkmcnt(0)
	v_mfma_f32_16x16x32_bf16 v[42:45], v[6:9], v[14:17], 0
	ds_read_b128 v[14:17], v41 offset:35392
	ds_read_b128 v[46:49], v41 offset:44608
	v_mfma_f32_16x16x32_bf16 v[10:13], v[6:9], v[10:13], 0
	s_waitcnt lgkmcnt(1)
	v_mfma_f32_16x16x32_bf16 v[14:17], v[2:5], v[14:17], v[10:13]
	s_waitcnt lgkmcnt(0)
	v_mfma_f32_16x16x32_bf16 v[10:13], v[2:5], v[46:49], v[42:45]
	s_nop 2
	global_load_dword v42, v39, s[56:57] offset:128
	global_load_dword v41, v39, s[48:49] offset:128
	global_load_dword v43, v39, s[50:51] offset:128
	s_waitcnt vmcnt(2)
	v_add_f32_e32 v14, v14, v42
	v_mul_f32_e32 v14, 0xbfb8aa3b, v14
	s_waitcnt vmcnt(0)
	v_exp_f32_e32 v14, v14
	v_add_f32_e32 v10, v10, v41
	v_mul_f32_e32 v10, 0xbfb8aa3b, v10
	v_add_f32_e32 v14, 1.0, v14
	v_rcp_f32_e32 v14, v14
	v_exp_f32_e32 v10, v10
	v_mul_f32_e32 v14, 0xc1000000, v14
	v_add_f32_e32 v10, 1.0, v10
	v_rcp_f32_e32 v10, v10
	v_add_f32_e32 v11, v11, v41
	v_mov_b32_e32 v48, v43
	global_load_dword v45, v0, s[40:41] offset:128
	global_load_dword v46, v0, s[40:41] offset:2176
	global_load_dword v47, v[28:29], off offset:128
	global_load_dword v44, v[28:29], off offset:2176
	global_load_dword v43, v39, s[46:47] offset:128
	v_mul_f32_e32 v49, v14, v48
	v_mul_f32_e32 v14, 0x3fb8aa3b, v49
	v_add_f32_e32 v49, v49, v49
	v_mul_f32_e32 v49, 0x3fb8aa3b, v49
	v_exp_f32_e32 v49, v49
	ds_read_u16 v53, v31 offset:320
	ds_read_u16 v54, v31 offset:448
	v_exp_f32_e32 v14, v14
	v_sub_f32_e32 v49, 1.0, v49
	v_max_f32_e32 v49, 0, v49
	v_cmp_gt_f32_e32 vcc, s31, v49
	v_mul_f32_e32 v50, 0x4f800000, v49
	s_waitcnt lgkmcnt(1)
	v_lshlrev_b32_e32 v53, 16, v53
	v_cndmask_b32_e32 v49, v49, v50, vcc
	v_sqrt_f32_e32 v50, v49
	s_waitcnt lgkmcnt(0)
	v_lshlrev_b32_e32 v54, 16, v54
	ds_write_b32 v37, v14 offset:53888
	v_mul_f32_e32 v11, 0xbfb8aa3b, v11
	v_add_u32_e32 v51, -1, v50
	v_fma_f32 v52, -v51, v50, v49
	v_cmp_ge_f32_e64 s[38:39], 0, v52
	v_add_u32_e32 v52, 1, v50
	v_exp_f32_e32 v11, v11
	v_cndmask_b32_e64 v51, v50, v51, s[38:39]
	v_fma_f32 v50, -v52, v50, v49
	v_cmp_lt_f32_e64 s[38:39], 0, v50
	v_add_f32_e32 v11, 1.0, v11
	v_rcp_f32_e32 v11, v11
	v_cndmask_b32_e64 v50, v51, v52, s[38:39]
	v_mul_f32_e32 v51, 0x37800000, v50
	v_cndmask_b32_e32 v50, v50, v51, vcc
	ds_read_u16 v51, v31 offset:64
	ds_read_u16 v52, v31 offset:192
	v_cmp_class_f32_e32 vcc, v49, v56
	s_waitcnt lgkmcnt(1)
; __device__ __forceinline__ float bf2f(bf16_t b) { return __uint_as_float(((unsigned)b) << 16); }
; __device__ __forceinline__ float sigmoidf_(float x) { return frcp(1.0f + fexp2(-x * LOG2E)); }
; template <int APPLY>
; __device__ void lru_item(PP p, int l, int bb, int ck, int nb, unsigned epoch) {
;     ...
;       const int ch = nk * 16 + fr, gch = nb * 64 + ch;
;       const float ba_ = p->lru_b_a[l * 512 + gch], bx_ = p->lru_b_x[l * 512 + gch];
;       const float sp = log1pf(__expf(-p->lru_lambda[l * 512 + gch]));
;       const float* cw = p->conv_w + (long)l * 4 * 512 + gch;
;       const float w0 = cw[0], w1 = cw[512], w2 = cw[1024], w3 = cw[1536], cb = p->conv_b[l * 512 + gch];
; #pragma unroll
;       for (int reg = 0; reg < 4; ++reg) {
;         const int tok = wid * 16 + 4 * fq + reg;
;         const float r = sigmoidf_(ra[reg] + ba_), ig = sigmoidf_(ia[reg] + bx_);
;         const float log_a = -8.0f * r * sp;
;         const float av = __expf(log_a);
;         const float mult = sqrtf(fmaxf(1.0f - __expf(2.0f * log_a), 0.f));
;         const float xc = cb + w0 * bf2f(cxs[(tok + 0) * 64 + ch]) + w1 * bf2f(cxs[(tok + 1) * 64 + ch]) +
;                          w2 * bf2f(cxs[(tok + 2) * 64 + ch]) + w3 * bf2f(cxs[(tok + 3) * 64 + ch]);
;         as_[tok * 64 + ch] = av;
;         bs_[tok * 64 + ch] = mult * ig * xc;
;       }
	v_lshlrev_b32_e32 v51, 16, v51
	s_waitcnt lgkmcnt(0)
	v_lshlrev_b32_e32 v52, 16, v52
	v_cndmask_b32_e32 v50, v50, v49, vcc
	v_or_b32_e32 v49, v38, v40
	v_mul_f32_e32 v10, v10, v50
	v_lshlrev_b32_e32 v14, 2, v49
	v_add_u32_e32 v49, s4, v14
	v_add_u32_e32 v14, 0, v14
	s_waitcnt vmcnt(0)
	v_fma_f32 v51, v45, v51, v43
	v_fmac_f32_e32 v51, v46, v52
	v_fmac_f32_e32 v51, v47, v53
	v_fmac_f32_e32 v51, v44, v54
	v_mul_f32_e32 v10, v51, v10
	ds_write_b32 v49, v10
	v_add_f32_e32 v10, v15, v42
	v_mul_f32_e32 v10, 0xbfb8aa3b, v10
	v_exp_f32_e32 v10, v10
	s_nop 0
	v_add_f32_e32 v10, 1.0, v10
	v_rcp_f32_e32 v10, v10
	s_nop 0
	v_mul_f32_e32 v10, 0xc1000000, v10
	v_mul_f32_e32 v10, v10, v48
	v_mul_f32_e32 v15, 0x3fb8aa3b, v10
	v_add_f32_e32 v10, v10, v10
	v_mul_f32_e32 v10, 0x3fb8aa3b, v10
	v_exp_f32_e32 v10, v10
	v_exp_f32_e32 v15, v15
	v_sub_f32_e32 v10, 1.0, v10
	v_max_f32_e32 v10, 0, v10
	v_cmp_gt_f32_e32 vcc, s31, v10
	v_mul_f32_e32 v49, 0x4f800000, v10
	ds_write_b32 v14, v15 offset:54016
	v_cndmask_b32_e32 v10, v10, v49, vcc
	v_sqrt_f32_e32 v49, v10
	s_nop 0
	v_add_u32_e32 v50, -1, v49
	v_fma_f32 v51, -v50, v49, v10
	v_cmp_ge_f32_e64 s[38:39], 0, v51
	v_add_u32_e32 v51, 1, v49
	s_nop 0
	v_cndmask_b32_e64 v50, v49, v50, s[38:39]
	v_fma_f32 v49, -v51, v49, v10
	v_cmp_lt_f32_e64 s[38:39], 0, v49
	s_nop 1
	v_cndmask_b32_e64 v49, v50, v51, s[38:39]
	v_fma_f32 v51, v45, v52, v43
	ds_read_u16 v52, v31 offset:576
	v_mul_f32_e32 v50, 0x37800000, v49
	v_cndmask_b32_e32 v49, v49, v50, vcc
	v_cmp_class_f32_e32 vcc, v10, v56
	v_fmac_f32_e32 v51, v46, v53
	v_fmac_f32_e32 v51, v47, v54
	v_cndmask_b32_e32 v10, v49, v10, vcc
	s_waitcnt lgkmcnt(0)
	v_lshlrev_b32_e32 v52, 16, v52
	v_or_b32_e32 v49, v36, v40
	v_fmac_f32_e32 v51, v44, v52
	v_mul_f32_e32 v10, v11, v10
	v_mul_f32_e32 v10, v51, v10
	v_lshl_add_u32 v11, v49, 2, s4
	ds_write_b32 v11, v10
	v_add_f32_e32 v10, v16, v42
	v_mul_f32_e32 v10, 0xbfb8aa3b, v10
	v_exp_f32_e32 v10, v10
	v_add_f32_e32 v11, v12, v41
	v_mul_f32_e32 v11, 0xbfb8aa3b, v11
	v_exp_f32_e32 v11, v11
	v_add_f32_e32 v10, 1.0, v10
	v_rcp_f32_e32 v10, v10
	v_lshl_add_u32 v50, v40, 1, v35
	v_add_f32_e32 v11, 1.0, v11
	v_rcp_f32_e32 v11, v11
	v_mul_f32_e32 v10, 0xc1000000, v10
	v_mul_f32_e32 v10, v10, v48
	v_mul_f32_e32 v12, 0x3fb8aa3b, v10
	v_add_f32_e32 v10, v10, v10
	v_mul_f32_e32 v10, 0x3fb8aa3b, v10
	v_exp_f32_e32 v10, v10
	v_exp_f32_e32 v12, v12
	v_sub_f32_e32 v10, 1.0, v10
	v_max_f32_e32 v10, 0, v10
	v_cmp_gt_f32_e32 vcc, s31, v10
	v_mul_f32_e32 v15, 0x4f800000, v10
	ds_write_b32 v14, v12 offset:54272
	v_cndmask_b32_e32 v10, v10, v15, vcc
	v_sqrt_f32_e32 v15, v10
	s_nop 0
	v_add_u32_e32 v16, -1, v15
	v_fma_f32 v49, -v16, v15, v10
	v_cmp_ge_f32_e64 s[38:39], 0, v49
	v_add_u32_e32 v49, 1, v15
	s_nop 0
	v_cndmask_b32_e64 v16, v15, v16, s[38:39]
	v_fma_f32 v15, -v49, v15, v10
	v_cmp_lt_f32_e64 s[38:39], 0, v15
	s_nop 1
	v_cndmask_b32_e64 v15, v16, v49, s[38:39]
	ds_read_u16 v49, v31 offset:704
	v_mul_f32_e32 v16, 0x37800000, v15
	v_cndmask_b32_e32 v15, v15, v16, vcc
	v_fma_f32 v16, v45, v53, v43
	v_cmp_class_f32_e32 vcc, v10, v56
	v_fmac_f32_e32 v16, v46, v54
	v_fmac_f32_e32 v16, v47, v52
	v_cndmask_b32_e32 v10, v15, v10, vcc
	s_waitcnt lgkmcnt(0)
	v_lshlrev_b32_e32 v49, 16, v49
	v_or_b32_e32 v15, v32, v40
	v_fmac_f32_e32 v16, v44, v49
	v_mul_f32_e32 v10, v11, v10
	v_mul_f32_e32 v10, v16, v10
	v_lshl_add_u32 v11, v15, 2, s4
	ds_write_b32 v11, v10
	v_add_f32_e32 v10, v17, v42
	v_mul_f32_e32 v10, 0xbfb8aa3b, v10
	v_exp_f32_e32 v10, v10
	v_add_f32_e32 v11, v13, v41
	v_mul_f32_e32 v11, 0xbfb8aa3b, v11
	v_exp_f32_e32 v11, v11
	v_add_f32_e32 v10, 1.0, v10
	v_rcp_f32_e32 v10, v10
	v_add_f32_e32 v11, 1.0, v11
	v_rcp_f32_e32 v11, v11
	v_mul_f32_e32 v10, 0xc1000000, v10
	v_mul_f32_e32 v10, v10, v48
	v_mul_f32_e32 v12, 0x3fb8aa3b, v10
	v_add_f32_e32 v10, v10, v10
	v_mul_f32_e32 v10, 0x3fb8aa3b, v10
	v_exp_f32_e32 v10, v10
	v_exp_f32_e32 v12, v12
	v_sub_f32_e32 v10, 1.0, v10
	v_max_f32_e32 v10, 0, v10
	v_cmp_gt_f32_e32 vcc, s31, v10
	v_mul_f32_e32 v13, 0x4f800000, v10
	ds_write_b32 v14, v12 offset:54528
	v_cndmask_b32_e32 v10, v10, v13, vcc
	v_sqrt_f32_e32 v13, v10
	s_nop 0
	v_add_u32_e32 v15, -1, v13
	v_fma_f32 v16, -v15, v13, v10
	v_cmp_ge_f32_e64 s[38:39], 0, v16
	v_add_u32_e32 v16, 1, v13
	s_nop 0
	v_cndmask_b32_e64 v15, v13, v15, s[38:39]
	v_fma_f32 v13, -v16, v13, v10
	v_cmp_lt_f32_e64 s[38:39], 0, v13
	s_nop 1
	v_cndmask_b32_e64 v13, v15, v16, s[38:39]
	v_mul_f32_e32 v15, 0x37800000, v13
	v_cndmask_b32_e32 v13, v13, v15, vcc
	ds_read_u16 v15, v50 offset:384
	v_cmp_class_f32_e32 vcc, v10, v56
	s_waitcnt lgkmcnt(0)
	v_lshlrev_b32_e32 v15, 16, v15
	v_fmac_f32_e32 v43, v45, v15
	ds_read_u16 v15, v31 offset:832
	v_fmac_f32_e32 v43, v46, v52
	v_cndmask_b32_e32 v10, v13, v10, vcc
	v_fmac_f32_e32 v43, v47, v49
	v_or_b32_e32 v13, v33, v40
	s_waitcnt lgkmcnt(0)
	v_lshlrev_b32_e32 v15, 16, v15
	v_fmac_f32_e32 v43, v44, v15
	v_mul_f32_e32 v10, v11, v10
	v_mul_f32_e32 v10, v43, v10
	v_lshl_add_u32 v11, v13, 2, s4
	ds_write_b32 v11, v10
	v_or_b32_e32 v11, 48, v30
	v_mul_u32_u24_e32 v10, 0x48, v11
	v_lshl_add_u32 v10, v10, 1, v34
	ds_read_b128 v[12:15], v10 offset:35328
	ds_read_b128 v[40:43], v10 offset:44544
	s_waitcnt lgkmcnt(1)
	v_mfma_f32_16x16x32_bf16 v[12:15], v[6:9], v[12:15], 0
	s_waitcnt lgkmcnt(0)
	v_mfma_f32_16x16x32_bf16 v[40:43], v[6:9], v[40:43], 0
	ds_read_b128 v[6:9], v10 offset:35392
	ds_read_b128 v[44:47], v10 offset:44608
	s_waitcnt lgkmcnt(1)
	v_mfma_f32_16x16x32_bf16 v[6:9], v[2:5], v[6:9], v[12:15]
	s_nop 2
	global_load_dword v13, v39, s[56:57] offset:192
	global_load_dword v12, v39, s[48:49] offset:192
	global_load_dword v10, v39, s[50:51] offset:192
	s_waitcnt vmcnt(2)
; __device__ __forceinline__ float bf2f(bf16_t b) { return __uint_as_float(((unsigned)b) << 16); }
; __device__ __forceinline__ float sigmoidf_(float x) { return frcp(1.0f + fexp2(-x * LOG2E)); }
; template <int APPLY>
; __device__ void lru_item(PP p, int l, int bb, int ck, int nb, unsigned epoch) {
;     ...
;       const int ch = nk * 16 + fr, gch = nb * 64 + ch;
;       const float ba_ = p->lru_b_a[l * 512 + gch], bx_ = p->lru_b_x[l * 512 + gch];
;       const float sp = log1pf(__expf(-p->lru_lambda[l * 512 + gch]));
;       const float* cw = p->conv_w + (long)l * 4 * 512 + gch;
;       const float w0 = cw[0], w1 = cw[512], w2 = cw[1024], w3 = cw[1536], cb = p->conv_b[l * 512 + gch];
; #pragma unroll
;       for (int reg = 0; reg < 4; ++reg) {
;         const int tok = wid * 16 + 4 * fq + reg;
;         const float r = sigmoidf_(ra[reg] + ba_), ig = sigmoidf_(ia[reg] + bx_);
;         const float log_a = -8.0f * r * sp;
;         const float av = __expf(log_a);
;         const float mult = sqrtf(fmaxf(1.0f - __expf(2.0f * log_a), 0.f));
;         const float xc = cb + w0 * bf2f(cxs[(tok + 0) * 64 + ch]) + w1 * bf2f(cxs[(tok + 1) * 64 + ch]) +
;                          w2 * bf2f(cxs[(tok + 2) * 64 + ch]) + w3 * bf2f(cxs[(tok + 3) * 64 + ch]);
;         as_[tok * 64 + ch] = av;
;         bs_[tok * 64 + ch] = mult * ig * xc;
;       }
;     }
;   }
;   __syncthreads();
	s_nop 0
	v_add_f32_e32 v6, v6, v13
	s_waitcnt lgkmcnt(0)
	v_mfma_f32_16x16x32_bf16 v[2:5], v[2:5], v[44:47], v[40:43]
	s_waitcnt vmcnt(0)
	v_mul_f32_e32 v6, 0xbfb8aa3b, v6
	v_exp_f32_e32 v6, v6
	s_nop 0
	v_add_f32_e32 v6, 1.0, v6
	v_rcp_f32_e32 v6, v6
	s_nop 2
	v_add_f32_e32 v2, v2, v12
	v_mul_f32_e32 v6, 0xc1000000, v6
	v_mul_f32_e32 v2, 0xbfb8aa3b, v2
	v_exp_f32_e32 v2, v2
	v_add_f32_e32 v3, v3, v12
	v_mov_b32_e32 v17, v10
	global_load_dword v14, v0, s[40:41] offset:192
	global_load_dword v15, v0, s[40:41] offset:2240
	global_load_dword v16, v[28:29], off offset:192
	global_load_dword v10, v[28:29], off offset:2240
	s_nop 0
	global_load_dword v0, v39, s[46:47] offset:192
	v_mul_f32_e32 v28, v6, v17
	v_mul_f32_e32 v6, 0x3fb8aa3b, v28
	v_add_f32_e32 v28, v28, v28
	v_mul_f32_e32 v28, 0x3fb8aa3b, v28
	v_exp_f32_e32 v28, v28
	ds_read_u16 v39, v31 offset:480
	v_add_f32_e32 v2, 1.0, v2
	v_rcp_f32_e32 v2, v2
	v_sub_f32_e32 v28, 1.0, v28
	v_max_f32_e32 v28, 0, v28
	v_cmp_gt_f32_e32 vcc, s31, v28
	v_mul_f32_e32 v29, 0x4f800000, v28
	v_exp_f32_e32 v6, v6
	v_cndmask_b32_e32 v28, v28, v29, vcc
	v_sqrt_f32_e32 v29, v28
	s_waitcnt lgkmcnt(0)
	v_lshlrev_b32_e32 v39, 16, v39
	ds_write_b32 v37, v6 offset:53952
	v_mul_f32_e32 v3, 0xbfb8aa3b, v3
	v_add_u32_e32 v30, -1, v29
	v_fma_f32 v34, -v30, v29, v28
	v_cmp_ge_f32_e64 s[38:39], 0, v34
	v_add_u32_e32 v34, 1, v29
	v_exp_f32_e32 v3, v3
	v_cndmask_b32_e64 v30, v29, v30, s[38:39]
	v_fma_f32 v29, -v34, v29, v28
	v_cmp_lt_f32_e64 s[38:39], 0, v29
	v_add_f32_e32 v3, 1.0, v3
	v_rcp_f32_e32 v3, v3
	v_cndmask_b32_e64 v29, v30, v34, s[38:39]
	v_mul_f32_e32 v30, 0x37800000, v29
	v_cndmask_b32_e32 v29, v29, v30, vcc
	ds_read_u16 v30, v31 offset:96
	ds_read_u16 v34, v31 offset:224
	v_cmp_class_f32_e32 vcc, v28, v56
	v_add_f32_e32 v4, v4, v12
	v_mul_f32_e32 v4, 0xbfb8aa3b, v4
	v_cndmask_b32_e32 v29, v29, v28, vcc
	v_or_b32_e32 v28, v38, v11
	ds_read_u16 v38, v31 offset:352
	s_waitcnt lgkmcnt(2)
	v_lshlrev_b32_e32 v30, 16, v30
	s_waitcnt lgkmcnt(1)
	v_lshlrev_b32_e32 v34, 16, v34
	v_mul_f32_e32 v2, v2, v29
	v_lshlrev_b32_e32 v6, 2, v28
	s_waitcnt lgkmcnt(0)
	v_lshlrev_b32_e32 v38, 16, v38
	v_add_u32_e32 v28, s4, v6
	v_exp_f32_e32 v4, v4
	s_waitcnt vmcnt(0)
	v_fma_f32 v30, v14, v30, v0
	v_fmac_f32_e32 v30, v15, v34
	v_fmac_f32_e32 v30, v16, v38
	v_fmac_f32_e32 v30, v10, v39
	v_mul_f32_e32 v2, v30, v2
	ds_write_b32 v28, v2
	v_add_f32_e32 v2, v7, v13
	v_mul_f32_e32 v2, 0xbfb8aa3b, v2
	v_exp_f32_e32 v2, v2
	v_fma_f32 v34, v14, v34, v0
	v_fmac_f32_e32 v34, v15, v38
	v_fmac_f32_e32 v34, v16, v39
	v_add_f32_e32 v2, 1.0, v2
	v_rcp_f32_e32 v2, v2
	v_add_f32_e32 v4, 1.0, v4
	v_rcp_f32_e32 v4, v4
	v_mul_f32_e32 v2, 0xc1000000, v2
	v_mul_f32_e32 v2, v2, v17
	v_mul_f32_e32 v7, 0x3fb8aa3b, v2
	v_add_f32_e32 v2, v2, v2
	v_mul_f32_e32 v2, 0x3fb8aa3b, v2
	v_exp_f32_e32 v2, v2
	v_exp_f32_e32 v7, v7
	v_sub_f32_e32 v2, 1.0, v2
	v_max_f32_e32 v2, 0, v2
	v_cmp_gt_f32_e32 vcc, s31, v2
	v_mul_f32_e32 v28, 0x4f800000, v2
	s_nop 0
	v_cndmask_b32_e32 v2, v2, v28, vcc
	v_sqrt_f32_e32 v28, v2
	s_nop 0
	v_add_u32_e32 v29, -1, v28
	v_fma_f32 v30, -v29, v28, v2
	v_cmp_ge_f32_e64 s[38:39], 0, v30
	v_add_u32_e32 v30, 1, v28
	s_nop 0
	v_cndmask_b32_e64 v29, v28, v29, s[38:39]
	v_fma_f32 v28, -v30, v28, v2
	v_cmp_lt_f32_e64 s[38:39], 0, v28
	s_nop 1
	v_cndmask_b32_e64 v28, v29, v30, s[38:39]
	v_mul_f32_e32 v29, 0x37800000, v28
	v_cndmask_b32_e32 v28, v28, v29, vcc
	v_cmp_class_f32_e32 vcc, v2, v56
	v_lshl_add_u32 v30, v11, 1, v35
	v_or_b32_e32 v29, v36, v11
	v_cndmask_b32_e32 v28, v28, v2, vcc
	ds_read_u16 v2, v31 offset:608
	v_mul_f32_e32 v3, v3, v28
	s_waitcnt lgkmcnt(0)
	v_lshlrev_b32_e32 v35, 16, v2
	v_fmac_f32_e32 v34, v10, v35
	v_add_u32_e32 v2, 0, v6
	v_mul_f32_e32 v3, v34, v3
	v_lshl_add_u32 v6, v29, 2, s4
	ds_write_b32 v2, v7 offset:54016
	ds_write_b32 v6, v3
	v_add_f32_e32 v3, v8, v13
	v_mul_f32_e32 v3, 0xbfb8aa3b, v3
	v_exp_f32_e32 v3, v3
	s_nop 0
	v_add_f32_e32 v3, 1.0, v3
	v_rcp_f32_e32 v3, v3
	s_nop 0
	v_mul_f32_e32 v3, 0xc1000000, v3
	v_mul_f32_e32 v3, v3, v17
	v_mul_f32_e32 v6, 0x3fb8aa3b, v3
	v_add_f32_e32 v3, v3, v3
	v_mul_f32_e32 v3, 0x3fb8aa3b, v3
	v_exp_f32_e32 v3, v3
	v_exp_f32_e32 v6, v6
	v_sub_f32_e32 v3, 1.0, v3
	v_max_f32_e32 v3, 0, v3
	v_cmp_gt_f32_e32 vcc, s31, v3
	v_mul_f32_e32 v7, 0x4f800000, v3
	ds_write_b32 v2, v6 offset:54272
	v_cndmask_b32_e32 v3, v3, v7, vcc
	v_sqrt_f32_e32 v7, v3
	s_nop 0
	v_add_u32_e32 v8, -1, v7
	v_fma_f32 v28, -v8, v7, v3
	v_cmp_ge_f32_e64 s[38:39], 0, v28
	v_add_u32_e32 v28, 1, v7
	s_nop 0
	v_cndmask_b32_e64 v8, v7, v8, s[38:39]
	v_fma_f32 v7, -v28, v7, v3
	v_cmp_lt_f32_e64 s[38:39], 0, v7
	s_nop 1
	v_cndmask_b32_e64 v7, v8, v28, s[38:39]
	ds_read_u16 v28, v31 offset:736
	v_mul_f32_e32 v8, 0x37800000, v7
	v_cndmask_b32_e32 v7, v7, v8, vcc
	v_fma_f32 v8, v14, v38, v0
	v_cmp_class_f32_e32 vcc, v3, v56
	v_fmac_f32_e32 v8, v15, v39
	v_fmac_f32_e32 v8, v16, v35
	v_cndmask_b32_e32 v3, v7, v3, vcc
	s_waitcnt lgkmcnt(0)
	v_lshlrev_b32_e32 v28, 16, v28
	v_or_b32_e32 v7, v32, v11
	v_fmac_f32_e32 v8, v10, v28
	v_mul_f32_e32 v3, v4, v3
	v_mul_f32_e32 v3, v8, v3
	v_lshl_add_u32 v4, v7, 2, s4
	ds_write_b32 v4, v3
	v_add_f32_e32 v3, v9, v13
	v_mul_f32_e32 v3, 0xbfb8aa3b, v3
	v_exp_f32_e32 v3, v3
	s_nop 0
	v_add_f32_e32 v3, 1.0, v3
	v_rcp_f32_e32 v4, v3
	v_add_f32_e32 v3, v5, v12
	v_mul_f32_e32 v3, 0xbfb8aa3b, v3
	v_exp_f32_e32 v3, v3
	v_mul_f32_e32 v4, 0xc1000000, v4
	v_mul_f32_e32 v5, v4, v17
	v_mul_f32_e32 v4, 0x3fb8aa3b, v5
	v_add_f32_e32 v5, v5, v5
	v_mul_f32_e32 v5, 0x3fb8aa3b, v5
	v_exp_f32_e32 v5, v5
	v_add_f32_e32 v3, 1.0, v3
	v_rcp_f32_e32 v3, v3
	v_exp_f32_e32 v4, v4
	v_sub_f32_e32 v5, 1.0, v5
	v_max_f32_e32 v5, 0, v5
	v_cmp_gt_f32_e32 vcc, s31, v5
	v_mul_f32_e32 v6, 0x4f800000, v5
	ds_write_b32 v2, v4 offset:54528
	v_cndmask_b32_e32 v5, v5, v6, vcc
	v_sqrt_f32_e32 v6, v5
	s_nop 0
	v_add_u32_e32 v7, -1, v6
	v_fma_f32 v8, -v7, v6, v5
	v_cmp_ge_f32_e64 s[38:39], 0, v8
	v_add_u32_e32 v8, 1, v6
	s_nop 0
	v_cndmask_b32_e64 v7, v6, v7, s[38:39]
	v_fma_f32 v6, -v8, v6, v5
	v_cmp_lt_f32_e64 s[38:39], 0, v6
	s_nop 1
	v_cndmask_b32_e64 v6, v7, v8, s[38:39]
	v_mul_f32_e32 v7, 0x37800000, v6
	v_cndmask_b32_e32 v6, v6, v7, vcc
	ds_read_u16 v7, v30 offset:384
	v_cmp_class_f32_e32 vcc, v5, v56
	s_waitcnt lgkmcnt(0)
	v_lshlrev_b32_e32 v7, 16, v7
	v_fmac_f32_e32 v0, v14, v7
	ds_read_u16 v7, v31 offset:864
	v_fmac_f32_e32 v0, v15, v35
	v_cndmask_b32_e32 v6, v6, v5, vcc
	v_fmac_f32_e32 v0, v16, v28
	v_or_b32_e32 v5, v33, v11
	s_waitcnt lgkmcnt(0)
	v_lshlrev_b32_e32 v7, 16, v7
	v_fmac_f32_e32 v0, v10, v7
	v_mul_f32_e32 v2, v3, v6
	v_mul_f32_e32 v0, v0, v2
	v_lshl_add_u32 v2, v5, 2, s4
	ds_write_b32 v2, v0
	v_or_b32_e32 v0, v25, v71
	v_lshlrev_b32_e32 v0, 2, v0
	v_add_u32_e32 v73, 0, v0
	v_add_u32_e32 v74, s4, v0
	s_waitcnt lgkmcnt(0)
	s_barrier
; template <int APPLY>
; __device__ void lru_item(PP p, int l, int bb, int ck, int nb, unsigned epoch) {
;     ...
;   {
;     const int ch = tid & 63, seg = tid >> 6;
;     float P = 1.f, hh = 0.f;
; #pragma unroll
;     for (int i = 0; i < 16; ++i) {
;       const int idx = (seg * 16 + i) * 64 + ch;
;       const float a = as_[idx], b = bs_[idx];
;       hh = a * hh + b; P *= a;
;       as_[idx] = P; bs_[idx] = hh;
;     }
;     segA[seg * 64 + ch] = P; segH[seg * 64 + ch] = hh;
;   }
	ds_read2st64_b32 v[80:81], v73 offset0:210 offset1:211
	ds_read2st64_b32 v[96:97], v74 offset1:1
	ds_read2st64_b32 v[82:83], v73 offset0:212 offset1:213
	ds_read2st64_b32 v[98:99], v74 offset0:2 offset1:3
	ds_read2st64_b32 v[84:85], v73 offset0:214 offset1:215
	ds_read2st64_b32 v[100:101], v74 offset0:4 offset1:5
	ds_read2st64_b32 v[86:87], v73 offset0:216 offset1:217
	ds_read2st64_b32 v[102:103], v74 offset0:6 offset1:7
	ds_read2st64_b32 v[88:89], v73 offset0:218 offset1:219
	ds_read2st64_b32 v[104:105], v74 offset0:8 offset1:9
	ds_read2st64_b32 v[90:91], v73 offset0:220 offset1:221
	ds_read2st64_b32 v[106:107], v74 offset0:10 offset1:11
	ds_read2st64_b32 v[92:93], v73 offset0:222 offset1:223
	ds_read2st64_b32 v[108:109], v74 offset0:12 offset1:13
	s_waitcnt lgkmcnt(6)
	ds_read2st64_b32 v[94:95], v73 offset0:224 offset1:225
	ds_read2st64_b32 v[110:111], v74 offset0:14 offset1:15
	s_lshl_b32 s4, s59, 16
	s_or_b32 s92, s4, s52
	s_lshl_b64 s[4:5], s[92:93], 3
	s_add_u32 s38, s42, s4
	s_addc_u32 s39, s43, s5
	v_cmp_gt_i32_e32 vcc, 64, v24
	v_lshl_add_u32 v0, v24, 2, 0
	v_add_u32_e32 v76, 0x1d200, v0
	v_add_u32_e32 v75, 0x1da00, v0
	s_waitcnt lgkmcnt(0)
	v_fma_f32 v96, 0, v80, v96
	v_fma_f32 v97, v96, v81, v97
	v_fma_f32 v98, v97, v82, v98
	v_fma_f32 v99, v98, v83, v99
	v_fma_f32 v100, v99, v84, v100
	v_fma_f32 v101, v100, v85, v101
	v_fma_f32 v102, v101, v86, v102
	v_fma_f32 v103, v102, v87, v103
	v_fma_f32 v104, v103, v88, v104
	v_fma_f32 v105, v104, v89, v105
	v_fma_f32 v106, v105, v90, v106
	v_fma_f32 v107, v106, v91, v107
	v_fma_f32 v108, v107, v92, v108
	v_fma_f32 v109, v108, v93, v109
	v_fma_f32 v110, v109, v94, v110
	v_fma_f32 v111, v110, v95, v111
	v_mul_f32_e32 v81, v80, v81
	v_mul_f32_e32 v82, v81, v82
	v_mul_f32_e32 v83, v82, v83
	v_mul_f32_e32 v84, v83, v84
	v_mul_f32_e32 v85, v84, v85
	v_mul_f32_e32 v86, v85, v86
	v_mul_f32_e32 v87, v86, v87
	v_mul_f32_e32 v88, v87, v88
	v_mul_f32_e32 v89, v88, v89
	v_mul_f32_e32 v90, v89, v90
	v_mul_f32_e32 v91, v90, v91
	v_mul_f32_e32 v92, v91, v92
	v_mul_f32_e32 v93, v92, v93
	v_mul_f32_e32 v94, v93, v94
	v_mul_f32_e32 v95, v94, v95
	ds_write2st64_b32 v74, v96, v97 offset1:1
	ds_write2st64_b32 v74, v98, v99 offset0:2 offset1:3
	ds_write2st64_b32 v74, v100, v101 offset0:4 offset1:5
	ds_write2st64_b32 v74, v102, v103 offset0:6 offset1:7
	ds_write2st64_b32 v74, v104, v105 offset0:8 offset1:9
	ds_write2st64_b32 v74, v106, v107 offset0:10 offset1:11
	ds_write2st64_b32 v74, v108, v109 offset0:12 offset1:13
	ds_write2st64_b32 v74, v110, v111 offset0:14 offset1:15
	ds_write2st64_b32 v73, v81, v82 offset0:211 offset1:212
	ds_write2st64_b32 v73, v83, v84 offset0:213 offset1:214
	ds_write2st64_b32 v73, v85, v86 offset0:215 offset1:216
	ds_write2st64_b32 v73, v87, v88 offset0:217 offset1:218
	ds_write2st64_b32 v73, v89, v90 offset0:219 offset1:220
	ds_write2st64_b32 v73, v91, v92 offset0:221 offset1:222
	ds_write2st64_b32 v73, v93, v94 offset0:223 offset1:224
	ds_write_b32 v73, v95 offset:57600
	ds_write_b32 v76, v95
	ds_write_b32 v75, v111
	s_waitcnt lgkmcnt(0)
	s_barrier
	s_and_saveexec_b64 s[40:41], vcc
	s_cbranch_execz .LBB0_124
	ds_read2st64_b32 v[2:3], v76 offset1:1
	ds_read2st64_b32 v[4:5], v75 offset1:1
	v_ashrrev_i32_e32 v25, 31, v24
	s_lshl_b32 s92, s58, 9
	s_waitcnt lgkmcnt(0)
	v_fma_f32 v4, 0, v2, v4
	v_fmac_f32_e32 v5, v4, v3
	v_mul_f32_e32 v4, v2, v3
	ds_read2st64_b32 v[2:3], v76 offset0:2 offset1:3
	ds_read2st64_b32 v[6:7], v75 offset0:2 offset1:3
	s_waitcnt lgkmcnt(0)
	v_fma_f32 v5, v5, v2, v6
	v_mul_f32_e32 v2, v4, v2
	v_fmac_f32_e32 v7, v5, v3
	v_mul_f32_e32 v6, v2, v3
	ds_read2st64_b32 v[2:3], v76 offset0:4 offset1:5
	ds_read2st64_b32 v[4:5], v75 offset0:4 offset1:5
	s_waitcnt lgkmcnt(0)
	v_fma_f32 v4, v7, v2, v4
	v_mul_f32_e32 v2, v6, v2
	v_fmac_f32_e32 v5, v4, v3
	v_mul_f32_e32 v4, v2, v3
	ds_read2st64_b32 v[2:3], v76 offset0:6 offset1:7
	ds_read2st64_b32 v[6:7], v75 offset0:6 offset1:7
	s_waitcnt lgkmcnt(0)
	v_fma_f32 v5, v5, v2, v6
	v_mul_f32_e32 v2, v4, v2
	v_fmac_f32_e32 v7, v5, v3
	v_lshl_add_u64 v[4:5], v[24:25], 0, s[92:93]
	v_mul_f32_e32 v2, v2, v3
	v_lshl_add_u64 v[4:5], v[4:5], 4, s[38:39]
	v_mov_b32_e32 v3, s71
	global_store_dwordx2 v[4:5], v[2:3], off sc1
	v_mov_b32_e32 v2, v7
	global_store_dwordx2 v[4:5], v[2:3], off offset:8 sc1

; template <int APPLY>
; __device__ void lru_item(PP p, int l, int bb, int ck, int nb, unsigned epoch) {
;     ...
;       float Ap = 1.f, Hp = 0.f;
; #pragma unroll
;       for (int i = 0; i < 8; ++i)
;         if (lo + i < hi) { const float a = __uint_as_float((unsigned)wa[i]), hvv = __uint_as_float((unsigned)wh[i]); Hp = a * Hp + hvv; Ap *= a; }
;       partA[w * 64 + ch] = Ap; partH[w * 64 + ch] = Hp;
;     }
;     __syncthreads();
;   }
;   if (tid < 64) {
;     const int ch = tid;
;     float carry = 0.f;
;     if (APPLY) {
; #pragma unroll
;       for (int w = 0; w < 8; ++w) carry = partA[w * 64 + ch] * carry + partH[w * 64 + ch];
;     }
;     float At = 1.f;
; #pragma unroll
;     for (int sg = 0; sg < 8; ++sg) {
;       cin[sg * 64 + ch] = carry;
;       const float a = segA[sg * 64 + ch];
;       carry = a * carry + segH[sg * 64 + ch]; At *= a;
;     }
.LBB0_144:
	s_or_b64 exec, exec, s[84:85]
	v_sub_u32_e32 v2, v77, v2
	v_cmp_lt_i32_e64 s[38:39], 0, v2
	v_fmac_f32_e32 v56, 0, v52
	s_nop 0
	v_cndmask_b32_e64 v3, 1.0, v52, s[38:39]
	v_cndmask_b32_e64 v4, 0, v56, s[38:39]
	v_mul_f32_e32 v5, v3, v50
	v_cmp_lt_i32_e64 s[38:39], 1, v2
	v_fmac_f32_e32 v54, v4, v50
	s_nop 0
	v_cndmask_b32_e64 v3, v3, v5, s[38:39]
	v_cndmask_b32_e64 v4, v4, v54, s[38:39]
	v_mul_f32_e32 v5, v3, v42
	v_cmp_lt_i32_e64 s[38:39], 2, v2
	v_fmac_f32_e32 v46, v4, v42
	s_nop 0
	v_cndmask_b32_e64 v3, v3, v5, s[38:39]
	v_cndmask_b32_e64 v4, v4, v46, s[38:39]
	v_mul_f32_e32 v5, v3, v36
	v_cmp_lt_i32_e64 s[38:39], 3, v2
	v_fmac_f32_e32 v40, v4, v36
	s_nop 0
	v_cndmask_b32_e64 v3, v3, v5, s[38:39]
	v_cndmask_b32_e64 v4, v4, v40, s[38:39]
	v_mul_f32_e32 v5, v3, v30
	v_cmp_lt_i32_e64 s[38:39], 4, v2
	v_fmac_f32_e32 v34, v4, v30
	s_nop 0
	v_cndmask_b32_e64 v3, v3, v5, s[38:39]
	v_cndmask_b32_e64 v4, v4, v34, s[38:39]
	v_mul_f32_e32 v5, v3, v24
	v_cmp_lt_i32_e64 s[38:39], 5, v2
	v_fmac_f32_e32 v28, v4, v24
	s_nop 0
	v_cndmask_b32_e64 v3, v3, v5, s[38:39]
	v_cndmask_b32_e64 v4, v4, v28, s[38:39]
	v_mul_f32_e32 v5, v3, v12
	v_cmp_lt_i32_e64 s[38:39], 6, v2
	v_fmac_f32_e32 v16, v4, v12
	s_nop 0
	v_cndmask_b32_e64 v3, v3, v5, s[38:39]
	v_cndmask_b32_e64 v4, v4, v16, s[38:39]
	v_mul_f32_e32 v5, v3, v6
	v_cmp_lt_i32_e64 s[38:39], 7, v2
	v_fmac_f32_e32 v10, v4, v6
	s_nop 0
	v_cndmask_b32_e64 v2, v3, v5, s[38:39]
	v_add_u32_e32 v3, 0x1ea00, v0
	v_cndmask_b32_e64 v4, v4, v10, s[38:39]
	ds_write_b32 v3, v2
	v_add_u32_e32 v2, 0x1f200, v0
	ds_write_b32 v2, v4
	s_waitcnt lgkmcnt(0)
	s_barrier
	s_and_saveexec_b64 s[38:39], vcc
	s_cbranch_execz .LBB0_146
	ds_read2st64_b32 v[80:81], v3 offset1:1
	ds_read2st64_b32 v[88:89], v2 offset1:1
	ds_read2st64_b32 v[82:83], v3 offset0:2 offset1:3
	ds_read2st64_b32 v[90:91], v2 offset0:2 offset1:3
	ds_read2st64_b32 v[84:85], v3 offset0:4 offset1:5
	ds_read2st64_b32 v[92:93], v2 offset0:4 offset1:5
	ds_read2st64_b32 v[86:87], v3 offset0:6 offset1:7
	ds_read2st64_b32 v[94:95], v2 offset0:6 offset1:7
	ds_read2st64_b32 v[96:97], v76 offset1:1
	ds_read2st64_b32 v[104:105], v75 offset1:1
	ds_read2st64_b32 v[98:99], v76 offset0:2 offset1:3
	ds_read2st64_b32 v[106:107], v75 offset0:2 offset1:3
	ds_read2st64_b32 v[100:101], v76 offset0:4 offset1:5
	ds_read2st64_b32 v[108:109], v75 offset0:4 offset1:5
	v_add_u32_e32 v8, 0x1e200, v0
	s_waitcnt lgkmcnt(6)
	ds_read_b32 v102, v76 offset:1536
	ds_read_b32 v110, v75 offset:1536
	v_fma_f32 v4, 0, v80, v88
	v_fmac_f32_e32 v89, v4, v81
	v_fma_f32 v4, v89, v82, v90
	v_fmac_f32_e32 v91, v4, v83
	v_fma_f32 v4, v91, v84, v92
	v_fmac_f32_e32 v93, v4, v85
	v_fma_f32 v2, v93, v86, v94
	v_fmac_f32_e32 v95, v2, v87
	s_waitcnt lgkmcnt(0)
	v_fma_f32 v2, v95, v96, v104
	ds_write2st64_b32 v8, v95, v2 offset1:1
	v_fmac_f32_e32 v105, v2, v97
	v_fma_f32 v2, v105, v98, v106
	ds_write2st64_b32 v8, v105, v2 offset0:2 offset1:3
	v_fmac_f32_e32 v107, v2, v99
	v_fma_f32 v2, v107, v100, v108
	ds_write2st64_b32 v8, v107, v2 offset0:4 offset1:5
	v_fmac_f32_e32 v109, v2, v101
	v_fmac_f32_e32 v110, v109, v102
	ds_write2st64_b32 v8, v109, v110 offset0:6 offset1:7

; template <int D, int MODE>
; __device__ void attn_item(PP p, int c, int l, int bb, int qb0, int h0) {
;     ...
;     if (sub == 0) {
;     __syncthreads();
;     {
;       if (!first) ATTN_ISSUE_LOADS_();
;       first = false;
;     ...
;     if (MODE != 1) break;
;     __syncthreads();
;     if (lane == 0) flags[wid] = wdone ? 1 : 0;
;     __syncthreads();
;     int all = 1;
; #pragma unroll
;     for (int i = 0; i < 8; ++i) all &= flags[i];
;     if (all || krow0 == 0) break;
;     krow0 -= 128; nk = 128;
.LBB0_168:
	s_mov_b64 s[100:101], 0
	s_cmp_eq_u32 s6, 0
	s_cbranch_scc1 .Lsb_nopf
	s_add_i32 s4, s6, 0xffffff80
	v_add_u32_e32 v28, s4, v87
	v_add_u32_e32 v6, 64, v28
	v_mad_i64_i32 v[4:5], s[4:5], v28, s91, v[74:75]
	v_mad_i64_i32 v[8:9], s[4:5], v6, s91, v[74:75]
	global_load_dwordx4 v[4:7], v[4:5], off offset:3584
	s_nop 0
	global_load_dwordx4 v[8:11], v[8:9], off offset:3584
	v_add_u32_e32 v64, v28, v87
	v_mad_i64_i32 v[28:29], s[4:5], v64, s91, v[78:79]
	v_add_co_u32_e32 v36, vcc, 0x4000, v28
	s_nop 1
	v_addc_co_u32_e32 v37, vcc, 0, v29, vcc
	global_load_dwordx4 v[28:31], v[28:29], off
	s_nop 0
	global_load_dwordx4 v[36:39], v[36:37], off offset:2560
	s_mov_b64 s[100:101], -1

; template <int D, int MODE>
; __device__ void attn_item(PP p, int c, int l, int bb, int qb0, int h0) {
;     ...
;     if (MODE != 1) break;
;     __syncthreads();
;     if (lane == 0) flags[wid] = wdone ? 1 : 0;
;     __syncthreads();
;     int all = 1;
; #pragma unroll
;     for (int i = 0; i < 8; ++i) all &= flags[i];
;     if (all || krow0 == 0) break;
;     krow0 -= 128; nk = 128;
.LBB0_174:
	s_barrier
	s_and_saveexec_b64 s[4:5], s[38:39]
	v_cndmask_b32_e64 v64, 0, 1, s[58:59]
	ds_write_b32 v94, v64
	s_or_b64 exec, exec, s[4:5]
	v_readlane_b32 s4, v255, 46
	s_waitcnt lgkmcnt(0)
	s_barrier
	v_mov_b32_e32 v64, s4
	ds_read_b128 v[64:67], v64
	v_readlane_b32 s4, v255, 48
	s_cmp_eq_u32 s6, 0
	v_add_u32_e32 v109, 0xffffff80, v109
	s_movk_i32 s8, 0x80
	s_waitcnt lgkmcnt(0)
	v_and_b32_e32 v64, v64, v65
	v_and_b32_e32 v64, v64, v66
	v_and_b32_e32 v68, v64, v67
	v_mov_b32_e32 v64, s4
	ds_read_b128 v[64:67], v64
	s_cselect_b64 s[4:5], -1, 0
	s_addk_i32 s6, 0xff80
	s_addk_i32 s13, 0xff80
	s_mov_b64 s[42:43], s[100:101]
	s_waitcnt lgkmcnt(0)
	v_and_b32_e32 v64, v68, v64
	v_and_b32_e32 v64, v64, v65
	v_and_b32_e32 v64, v64, v66
	v_and_b32_e32 v64, v64, v67
	v_and_b32_e32 v64, 1, v64
	v_cmp_eq_u32_e32 vcc, 1, v64
	s_or_b64 s[4:5], vcc, s[4:5]
	s_andn2_b64 vcc, exec, s[4:5]
	s_cbranch_vccz .Lsb_exit
	s_mov_b64 s[40:41], s[58:59]
	s_branch .LBB0_155
.Lsb_exit:
	s_waitcnt vmcnt(0)
	s_branch .LBB0_209

;   __device__ __forceinline__ void epilogue(int u, f32x4 (&acc)[2][2][4][2]) const {
;     const bf16_t *A, *Bt; const float* ssq; bf16_t* out; int ldo;
;     locate(u, A, Bt, ssq, out, ldo);
;     const int tcol = (int)((out - p->proj) % INW);
;     const bool gate_tile = (ldo == INW) && tcol >= C_MRG;
;     char* grow = (char*)(out - tcol);
;     const int gcol0 = 2 * C_MRG + (tcol - C_MRG);
;     const int t_ = otid(), w_ = t_ >> 6, l_ = t_ & 63, wr = w_ >> 2, wc = w_ & 3, fr = l_ & 15, fq = l_ >> 4;
.LBB0_381:
	s_lshl_b64 s[4:5], s[4:5], 1
	s_add_u32 s52, s42, s4
	s_addc_u32 s53, s43, s5
	s_sub_u32 s4, s52, s46
	s_subb_u32 s5, s53, s47
	s_ashr_i64 s[42:43], s[4:5], 1
	s_mul_i32 s44, s43, 0x83759f23
	s_mul_hi_u32 s45, s42, 0x83759f23
	s_mul_hi_u32 s31, s43, 0x83759f23
	s_add_u32 s44, s44, s45
	s_mul_i32 s13, s42, 0x3759f229
	s_addc_u32 s31, s31, 0
	s_mul_hi_u32 s4, s42, 0x3759f229
	s_add_u32 s13, s13, s44
	s_addc_u32 s4, s4, 0
	s_add_u32 s4, s31, s4
	s_addc_u32 s13, 0, 0
	s_mul_i32 s44, s43, 0x3759f229
	s_mul_hi_u32 s31, s43, 0x3759f229
	s_add_u32 s4, s44, s4
	s_addc_u32 s13, s31, s13
	s_ashr_i32 s5, s5, 31
	s_mul_i32 s31, s5, 0x3759f229
	s_mul_hi_u32 s44, s5, 0x83759f23
	s_add_i32 s31, s44, s31
	s_mul_i32 s5, s5, 0x83759f23
	s_add_i32 s31, s31, s5
	s_add_u32 s4, s4, s5
	s_addc_u32 s5, s13, s31
	s_ashr_i64 s[44:45], s[4:5], 11
	s_lshr_b32 s4, s5, 31
	s_add_u32 s4, s44, s4
	s_addc_u32 s5, s45, 0
	s_mulk_i32 s5, 0x2500
	s_mul_hi_u32 s13, s4, 0x2500
	s_add_i32 s13, s13, s5
	s_mulk_i32 s4, 0x2500
	s_sub_u32 s44, s42, s4
	s_subb_u32 s45, s43, s13
	v_mov_b64_e32 v[134:135], 0x1500
	v_cmp_lt_i64_e32 vcc, s[44:45], v[134:135]
	s_xor_b64 s[4:5], s[56:57], -1
	s_or_b64 s[56:57], s[4:5], vcc
	s_and_b64 vcc, exec, s[56:57]
	s_cbranch_vccnz .Lb16_fast
	s_getreg_b32 s4, hwreg(HW_REG_HW_ID, 0, 6)
	s_lshl_b32 s4, s4, 2
	s_and_b32 s4, s4, 0xfc
	s_add_i32 s4, s4, 0
	s_add_i32 s4, s4, 0x21c00
	v_mov_b32_e32 v0, s4
	ds_read_b32 v0, v0
	s_mov_b32 s4, -1
	s_mov_b64 s[42:43], -1
	v_mbcnt_lo_u32_b32 v134, s4, 0
	v_mbcnt_hi_u32_b32 v134, s4, v134
	s_waitcnt lgkmcnt(0)
	v_lshl_add_u32 v0, v0, 6, v134
	s_waitcnt vmcnt(16)
	v_fmamk_f32 v134, v146, 0x3a800000, v242
	v_cmp_gt_f32_e32 vcc, s79, v134
	v_mul_f32_e32 v135, 0x4b800000, v134
	s_nop 0
	v_cndmask_b32_e32 v134, v134, v135, vcc
	v_rsq_f32_e32 v134, v134
	s_nop 0
	v_mul_f32_e32 v135, 0x45800000, v134
	v_cndmask_b32_e32 v140, v134, v135, vcc
	v_pk_mul_f32 v[142:143], v[140:141], v[126:127] op_sel_hi:[0,1]
	v_pk_mul_f32 v[128:129], v[140:141], v[128:129] op_sel_hi:[0,1]
	s_and_b64 vcc, exec, s[56:57]
	s_cbranch_vccz .LBB0_383
	v_cvt_pk_bf16_f32 v126, v142, v143
	v_cvt_pk_bf16_f32 v127, v128, v129
	s_mov_b64 s[42:43], 0

; __device__ __forceinline__ float sigmoidf_(float x) { return frcp(1.0f + fexp2(-x * LOG2E)); }
;   __device__ __forceinline__ void epilogue(int u, f32x4 (&acc)[2][2][4][2]) const {
;     ...
;     const int t_ = otid(), w_ = t_ >> 6, l_ = t_ & 63, wr = w_ >> 2, wc = w_ & 3, fr = l_ & 15, fq = l_ >> 4;
; #pragma unroll
;     for (int ai = 0; ai < 2; ++ai)
; #pragma unroll
;       for (int m = 0; m < 4; ++m) {
;         const int r = ai * 128 + wr * 64 + m * 16 + fr;
;         const float rs = rsqrtf(ssqp[ai][m] * (1.0f / DM) + EPS);
;         const unsigned ob = (unsigned)r * (unsigned)ldo + wc * 32 + fq * 8;
; #pragma unroll
;         for (int bj = 0; bj < 2; ++bj) {
;           uint4 pk; uint2 gq;
; #pragma unroll
;           for (int n = 0; n < 2; ++n) {
;             f32x4 v = acc[ai][bj][m][n];
;             v[0] *= rs; v[1] *= rs; v[2] *= rs; v[3] *= rs;
;             if (gate_tile) {
;               const unsigned q0 = (unsigned)fminf(sigmoidf_(v[0]) * 256.f, 255.f), q1 = (unsigned)fminf(sigmoidf_(v[1]) * 256.f, 255.f);
;               const unsigned q2 = (unsigned)fminf(sigmoidf_(v[2]) * 256.f, 255.f), q3 = (unsigned)fminf(sigmoidf_(v[3]) * 256.f, 255.f);
;               const unsigned w = q0 | (q1 << 8) | (q2 << 16) | (q3 << 24);
;               if (n == 0) gq.x = w; else gq.y = w;
;             } else {
;               if (n == 0) { pk.x = cvt_pk_bf16(v[0], v[1]); pk.y = cvt_pk_bf16(v[2], v[3]); }
;               else { pk.z = cvt_pk_bf16(v[0], v[1]); pk.w = cvt_pk_bf16(v[2], v[3]); }
;             }
;           }
;           if (!dry) {
;             if (gate_tile) *(uint2*)(grow + ((unsigned)r * (unsigned)(INW * 2) + (unsigned)(gcol0 + bj * 128 + wc * 32 + fq * 8))) = gq;
;             else *(uint4*)(out + (ob + bj * 128)) = pk;
;           }
.Lb16_fast:
	s_getreg_b32 s4, hwreg(HW_REG_HW_ID, 0, 6)
	s_lshl_b32 s4, s4, 2
	s_and_b32 s4, s4, 0xfc
	s_add_i32 s4, s4, 0
	s_add_i32 s4, s4, 0x21c00
	v_mov_b32_e32 v0, s4
	ds_read_b32 v0, v0
	s_mov_b32 s4, -1
	s_mov_b64 s[42:43], -1
	v_mbcnt_lo_u32_b32 v134, s4, 0
	v_mbcnt_hi_u32_b32 v134, s4, v134
	s_waitcnt lgkmcnt(0)
	v_lshl_add_u32 v0, v0, 6, v134
	s_waitcnt vmcnt(16)
	v_fmamk_f32 v134, v146, 0x3a800000, v242
	v_cmp_gt_f32_e32 vcc, s79, v134
	v_mul_f32_e32 v135, 0x4b800000, v134
	s_nop 0
	v_cndmask_b32_e32 v134, v134, v135, vcc
	v_rsq_f32_e32 v134, v134
	s_nop 0
	v_mul_f32_e32 v135, 0x45800000, v134
	v_cndmask_b32_e32 v140, v134, v135, vcc
	v_pk_mul_f32 v[142:143], v[140:141], v[126:127] op_sel_hi:[0,1]
	v_pk_mul_f32 v[128:129], v[140:141], v[128:129] op_sel_hi:[0,1]
	v_cvt_pk_bf16_f32 v126, v142, v143
	v_cvt_pk_bf16_f32 v127, v128, v129
	s_mov_b64 s[42:43], 0
	v_mov_b32_e32 v141, v140
	v_pk_mul_f32 v[142:143], v[140:141], v[122:123]
	v_pk_mul_f32 v[122:123], v[140:141], v[124:125]
	v_cndmask_b32_e64 v124, 0, 1, s[56:57]
	v_cmp_ne_u32_e64 s[42:43], 1, v124
	s_mov_b64 s[4:5], -1
	v_cvt_pk_bf16_f32 v128, v142, v143
	v_cvt_pk_bf16_f32 v129, v122, v123
	s_mov_b64 s[4:5], 0
	s_lshl_b64 s[4:5], s[44:45], 1
	s_sub_u32 s46, s52, s4
	v_and_b32_e32 v122, 15, v0
	v_ashrrev_i32_e32 v123, 2, v0
	s_movk_i32 s4, 0xffc0
	v_and_or_b32 v122, v123, s4, v122
	v_lshrrev_b32_e32 v123, 1, v0
	v_and_b32_e32 v124, 0x78, v123
	v_mul_lo_u32 v142, v122, s30
	s_subb_u32 s47, s53, s5
	v_or_b32_e32 v0, v142, v124
	s_mov_b64 s[4:5], -1
	v_lshl_add_u64 v[134:135], v[0:1], 1, s[52:53]
	global_store_dwordx4 v[134:135], v[126:129], off
	s_mov_b64 s[4:5], 0
	s_add_i32 s13, s44, 0x1500
	v_and_b32_e32 v125, 0x60, v123
	v_and_b32_e32 v123, 24, v123
	v_add3_u32 v125, s13, v125, v123
	v_mul_lo_u32 v143, v122, s91
	v_add_u32_e32 v154, v125, v143
	v_pk_mul_f32 v[122:123], v[140:141], v[118:119]
	v_pk_mul_f32 v[120:121], v[140:141], v[120:121]
	s_mov_b64 s[4:5], -1
	v_cvt_pk_bf16_f32 v118, v122, v123
	v_cvt_pk_bf16_f32 v119, v120, v121
	s_mov_b64 s[4:5], 0
	v_pk_mul_f32 v[122:123], v[140:141], v[114:115]
	v_pk_mul_f32 v[114:115], v[140:141], v[116:117]
	s_mov_b64 s[4:5], -1
	v_cvt_pk_bf16_f32 v120, v122, v123
	v_cvt_pk_bf16_f32 v121, v114, v115
	s_mov_b64 s[4:5], -1
	v_lshl_add_u64 v[114:115], v[0:1], 1, s[52:53]
	global_store_dwordx4 v[114:115], v[118:121], off offset:256
	v_fmamk_f32 v0, v147, 0x3a800000, v242
	v_mul_f32_e32 v114, 0x4b800000, v0
	v_cmp_gt_f32_e64 s[44:45], s79, v0
	s_mov_b64 s[4:5], -1
	v_cndmask_b32_e64 v0, v0, v114, s[44:45]
	v_rsq_f32_e32 v0, v0
	s_nop 0
	v_mul_f32_e32 v114, 0x45800000, v0
	v_cndmask_b32_e64 v114, v0, v114, s[44:45]
	v_pk_mul_f32 v[116:117], v[114:115], v[110:111] op_sel_hi:[0,1]
	v_pk_mul_f32 v[112:113], v[114:115], v[112:113] op_sel_hi:[0,1]
	v_cvt_pk_bf16_f32 v110, v116, v117
	v_cvt_pk_bf16_f32 v111, v112, v113
	s_mov_b64 s[4:5], 0
	v_mov_b32_e32 v115, v114
	v_pk_mul_f32 v[116:117], v[114:115], v[106:107]
	v_pk_mul_f32 v[106:107], v[114:115], v[108:109]
	s_mov_b64 s[4:5], -1
	v_cvt_pk_bf16_f32 v112, v116, v117
	v_cvt_pk_bf16_f32 v113, v106, v107
	s_mov_b64 s[4:5], 0
	s_lshl_b32 s13, s30, 4
	v_add_u32_e32 v108, s13, v142
	v_or_b32_e32 v0, v108, v124
	s_mov_b64 s[4:5], -1
	v_lshl_add_u64 v[106:107], v[0:1], 1, s[52:53]
	s_mov_b64 s[4:5], 0
	global_store_dwordx4 v[106:107], v[110:113], off
	v_add_u32_e32 v109, 0x4a000, v143
	v_add_u32_e32 v116, v109, v125
	v_pk_mul_f32 v[106:107], v[114:115], v[102:103]
	v_pk_mul_f32 v[104:105], v[114:115], v[104:105]
	s_mov_b64 s[4:5], -1
	v_cvt_pk_bf16_f32 v102, v106, v107
	v_cvt_pk_bf16_f32 v103, v104, v105
	s_mov_b64 s[4:5], 0
	v_pk_mul_f32 v[106:107], v[114:115], v[98:99]
	v_pk_mul_f32 v[98:99], v[114:115], v[100:101]
	s_mov_b64 s[4:5], -1
	v_cvt_pk_bf16_f32 v104, v106, v107
	v_cvt_pk_bf16_f32 v105, v98, v99
	s_mov_b64 s[4:5], -1
	v_lshl_add_u64 v[98:99], v[0:1], 1, s[52:53]
	global_store_dwordx4 v[98:99], v[102:105], off offset:256
	v_fmamk_f32 v0, v148, 0x3a800000, v242
	v_mul_f32_e32 v98, 0x4b800000, v0
	v_cmp_gt_f32_e64 s[44:45], s79, v0
	s_mov_b64 s[4:5], -1
	v_cndmask_b32_e64 v0, v0, v98, s[44:45]
	v_rsq_f32_e32 v0, v0
	s_nop 0
	v_mul_f32_e32 v98, 0x45800000, v0
	v_cndmask_b32_e64 v98, v0, v98, s[44:45]
	v_pk_mul_f32 v[100:101], v[98:99], v[94:95] op_sel_hi:[0,1]
	v_pk_mul_f32 v[96:97], v[98:99], v[96:97] op_sel_hi:[0,1]
	v_cvt_pk_bf16_f32 v94, v100, v101
	v_cvt_pk_bf16_f32 v95, v96, v97
	s_mov_b64 s[4:5], 0
	v_mov_b32_e32 v99, v98
	v_pk_mul_f32 v[100:101], v[98:99], v[90:91]
	v_pk_mul_f32 v[90:91], v[98:99], v[92:93]
	s_mov_b64 s[4:5], -1
	v_cvt_pk_bf16_f32 v96, v100, v101
	v_cvt_pk_bf16_f32 v97, v90, v91
	s_mov_b64 s[4:5], 0
	v_add_u32_e32 v92, s13, v108
	v_or_b32_e32 v0, v92, v124
	s_mov_b64 s[4:5], -1
	v_lshl_add_u64 v[90:91], v[0:1], 1, s[52:53]
	s_mov_b64 s[4:5], 0
	global_store_dwordx4 v[90:91], v[94:97], off
	v_add_u32_e32 v93, 0x4a000, v109
	v_add_u32_e32 v100, v93, v125
	v_pk_mul_f32 v[90:91], v[98:99], v[86:87]
	v_pk_mul_f32 v[88:89], v[98:99], v[88:89]
	s_mov_b64 s[4:5], -1
	v_cvt_pk_bf16_f32 v86, v90, v91
	v_cvt_pk_bf16_f32 v87, v88, v89
	s_mov_b64 s[4:5], 0
	v_pk_mul_f32 v[90:91], v[98:99], v[82:83]
	v_pk_mul_f32 v[82:83], v[98:99], v[84:85]
	s_mov_b64 s[4:5], -1
	v_cvt_pk_bf16_f32 v88, v90, v91
	v_cvt_pk_bf16_f32 v89, v82, v83
	s_mov_b64 s[4:5], -1
	v_lshl_add_u64 v[82:83], v[0:1], 1, s[52:53]
	global_store_dwordx4 v[82:83], v[86:89], off offset:256
	v_fmamk_f32 v0, v149, 0x3a800000, v242
	v_mul_f32_e32 v82, 0x4b800000, v0
	v_cmp_gt_f32_e64 s[44:45], s79, v0
	s_mov_b64 s[4:5], -1
	v_cndmask_b32_e64 v0, v0, v82, s[44:45]
	v_rsq_f32_e32 v0, v0
	s_nop 0
	v_mul_f32_e32 v82, 0x45800000, v0
; __device__ __forceinline__ float sigmoidf_(float x) { return frcp(1.0f + fexp2(-x * LOG2E)); }
;   __device__ __forceinline__ void epilogue(int u, f32x4 (&acc)[2][2][4][2]) const {
;     ...
;     const int t_ = otid(), w_ = t_ >> 6, l_ = t_ & 63, wr = w_ >> 2, wc = w_ & 3, fr = l_ & 15, fq = l_ >> 4;
; #pragma unroll
;     for (int ai = 0; ai < 2; ++ai)
; #pragma unroll
;       for (int m = 0; m < 4; ++m) {
;         const int r = ai * 128 + wr * 64 + m * 16 + fr;
;         const float rs = rsqrtf(ssqp[ai][m] * (1.0f / DM) + EPS);
;         const unsigned ob = (unsigned)r * (unsigned)ldo + wc * 32 + fq * 8;
; #pragma unroll
;         for (int bj = 0; bj < 2; ++bj) {
;           uint4 pk; uint2 gq;
; #pragma unroll
;           for (int n = 0; n < 2; ++n) {
;             f32x4 v = acc[ai][bj][m][n];
;             v[0] *= rs; v[1] *= rs; v[2] *= rs; v[3] *= rs;
;             if (gate_tile) {
;               const unsigned q0 = (unsigned)fminf(sigmoidf_(v[0]) * 256.f, 255.f), q1 = (unsigned)fminf(sigmoidf_(v[1]) * 256.f, 255.f);
;               const unsigned q2 = (unsigned)fminf(sigmoidf_(v[2]) * 256.f, 255.f), q3 = (unsigned)fminf(sigmoidf_(v[3]) * 256.f, 255.f);
;               const unsigned w = q0 | (q1 << 8) | (q2 << 16) | (q3 << 24);
;               if (n == 0) gq.x = w; else gq.y = w;
;             } else {
;               if (n == 0) { pk.x = cvt_pk_bf16(v[0], v[1]); pk.y = cvt_pk_bf16(v[2], v[3]); }
;               else { pk.z = cvt_pk_bf16(v[0], v[1]); pk.w = cvt_pk_bf16(v[2], v[3]); }
;             }
;           }
;           if (!dry) {
;             if (gate_tile) *(uint2*)(grow + ((unsigned)r * (unsigned)(INW * 2) + (unsigned)(gcol0 + bj * 128 + wc * 32 + fq * 8))) = gq;
;             else *(uint4*)(out + (ob + bj * 128)) = pk;
;           }
	v_cndmask_b32_e64 v82, v0, v82, s[44:45]
	v_pk_mul_f32 v[84:85], v[82:83], v[78:79] op_sel_hi:[0,1]
	v_pk_mul_f32 v[80:81], v[82:83], v[80:81] op_sel_hi:[0,1]
	v_cvt_pk_bf16_f32 v78, v84, v85
	v_cvt_pk_bf16_f32 v79, v80, v81
	s_mov_b64 s[4:5], 0
	v_mov_b32_e32 v83, v82
	v_pk_mul_f32 v[84:85], v[82:83], v[74:75]
	v_pk_mul_f32 v[74:75], v[82:83], v[76:77]
	s_mov_b64 s[4:5], -1
	v_cvt_pk_bf16_f32 v80, v84, v85
	v_cvt_pk_bf16_f32 v81, v74, v75
	s_mov_b64 s[4:5], 0
	v_add_u32_e32 v76, s13, v92
	v_or_b32_e32 v0, v76, v124
	s_mov_b64 s[4:5], -1
	v_lshl_add_u64 v[74:75], v[0:1], 1, s[52:53]
	s_mov_b64 s[4:5], 0
	global_store_dwordx4 v[74:75], v[78:81], off
	v_add_u32_e32 v77, 0x4a000, v93
	v_add_u32_e32 v84, v77, v125
	v_pk_mul_f32 v[74:75], v[82:83], v[70:71]
	v_pk_mul_f32 v[72:73], v[82:83], v[72:73]
	s_mov_b64 s[4:5], -1
	v_cvt_pk_bf16_f32 v70, v74, v75
	v_cvt_pk_bf16_f32 v71, v72, v73
	s_mov_b64 s[4:5], 0
	v_pk_mul_f32 v[74:75], v[82:83], v[66:67]
	v_pk_mul_f32 v[66:67], v[82:83], v[68:69]
	s_mov_b64 s[4:5], -1
	v_cvt_pk_bf16_f32 v72, v74, v75
	v_cvt_pk_bf16_f32 v73, v66, v67
	s_mov_b64 s[4:5], -1
	v_lshl_add_u64 v[66:67], v[0:1], 1, s[52:53]
	global_store_dwordx4 v[66:67], v[70:73], off offset:256
	v_fmamk_f32 v0, v150, 0x3a800000, v242
	v_mul_f32_e32 v66, 0x4b800000, v0
	v_cmp_gt_f32_e64 s[44:45], s79, v0
	s_mov_b64 s[4:5], -1
	v_cndmask_b32_e64 v0, v0, v66, s[44:45]
	v_rsq_f32_e32 v0, v0
	s_nop 0
	v_mul_f32_e32 v66, 0x45800000, v0
	v_cndmask_b32_e64 v66, v0, v66, s[44:45]
	v_pk_mul_f32 v[68:69], v[66:67], v[62:63] op_sel_hi:[0,1]
	v_pk_mul_f32 v[64:65], v[66:67], v[64:65] op_sel_hi:[0,1]
	v_cvt_pk_bf16_f32 v62, v68, v69
	v_cvt_pk_bf16_f32 v63, v64, v65
	s_mov_b64 s[4:5], 0
	v_mov_b32_e32 v67, v66
	v_pk_mul_f32 v[68:69], v[66:67], v[58:59]
	v_pk_mul_f32 v[58:59], v[66:67], v[60:61]
	s_mov_b64 s[4:5], -1
	v_cvt_pk_bf16_f32 v64, v68, v69
	v_cvt_pk_bf16_f32 v65, v58, v59
	s_mov_b64 s[4:5], 0
	s_mul_i32 s4, s30, 0x50
	v_add_u32_e32 v60, s4, v76
	v_or_b32_e32 v0, v60, v124
	s_mov_b64 s[4:5], -1
	v_lshl_add_u64 v[58:59], v[0:1], 1, s[52:53]
	s_mov_b64 s[4:5], 0
	global_store_dwordx4 v[58:59], v[62:65], off
	v_add_u32_e32 v61, 0x172000, v77
	v_add_u32_e32 v68, v61, v125
	v_pk_mul_f32 v[58:59], v[66:67], v[54:55]
	v_pk_mul_f32 v[56:57], v[66:67], v[56:57]
	s_mov_b64 s[4:5], -1
	v_cvt_pk_bf16_f32 v54, v58, v59
	v_cvt_pk_bf16_f32 v55, v56, v57
	s_mov_b64 s[4:5], 0
	v_pk_mul_f32 v[58:59], v[66:67], v[50:51]
	v_pk_mul_f32 v[50:51], v[66:67], v[52:53]
	s_mov_b64 s[4:5], -1
	v_cvt_pk_bf16_f32 v56, v58, v59
	v_cvt_pk_bf16_f32 v57, v50, v51
	s_mov_b64 s[4:5], -1
	v_lshl_add_u64 v[50:51], v[0:1], 1, s[52:53]
	global_store_dwordx4 v[50:51], v[54:57], off offset:256
	v_fmamk_f32 v0, v151, 0x3a800000, v242
	v_mul_f32_e32 v50, 0x4b800000, v0
	v_cmp_gt_f32_e64 s[44:45], s79, v0
	s_mov_b64 s[4:5], -1
	v_cndmask_b32_e64 v0, v0, v50, s[44:45]
	v_rsq_f32_e32 v0, v0
	s_nop 0
	v_mul_f32_e32 v50, 0x45800000, v0
	v_cndmask_b32_e64 v50, v0, v50, s[44:45]
	v_pk_mul_f32 v[52:53], v[50:51], v[46:47] op_sel_hi:[0,1]
	v_pk_mul_f32 v[48:49], v[50:51], v[48:49] op_sel_hi:[0,1]
	v_cvt_pk_bf16_f32 v46, v52, v53
	v_cvt_pk_bf16_f32 v47, v48, v49
	s_mov_b64 s[4:5], 0
	v_mov_b32_e32 v51, v50
	v_pk_mul_f32 v[52:53], v[50:51], v[42:43]
	v_pk_mul_f32 v[42:43], v[50:51], v[44:45]
	s_mov_b64 s[4:5], -1
	v_cvt_pk_bf16_f32 v48, v52, v53
	v_cvt_pk_bf16_f32 v49, v42, v43
	s_mov_b64 s[4:5], 0
	v_add_u32_e32 v44, s13, v60
	v_or_b32_e32 v0, v44, v124
	s_mov_b64 s[4:5], -1
	v_lshl_add_u64 v[42:43], v[0:1], 1, s[52:53]
	s_mov_b64 s[4:5], 0
	global_store_dwordx4 v[42:43], v[46:49], off
	v_add_u32_e32 v45, 0x4a000, v61
	v_add_u32_e32 v52, v45, v125
	v_pk_mul_f32 v[42:43], v[50:51], v[38:39]
	v_pk_mul_f32 v[40:41], v[50:51], v[40:41]
	s_mov_b64 s[4:5], -1
	v_cvt_pk_bf16_f32 v38, v42, v43
	v_cvt_pk_bf16_f32 v39, v40, v41
	s_mov_b64 s[4:5], 0
	v_pk_mul_f32 v[42:43], v[50:51], v[34:35]
	v_pk_mul_f32 v[34:35], v[50:51], v[36:37]
	s_mov_b64 s[4:5], -1
	v_cvt_pk_bf16_f32 v40, v42, v43
	v_cvt_pk_bf16_f32 v41, v34, v35
	s_mov_b64 s[4:5], -1
	v_lshl_add_u64 v[34:35], v[0:1], 1, s[52:53]
	global_store_dwordx4 v[34:35], v[38:41], off offset:256
	v_fmamk_f32 v0, v152, 0x3a800000, v242
	v_mul_f32_e32 v34, 0x4b800000, v0
	v_cmp_gt_f32_e64 s[44:45], s79, v0
	s_mov_b64 s[4:5], -1
	v_cndmask_b32_e64 v0, v0, v34, s[44:45]
	v_rsq_f32_e32 v0, v0
	s_nop 0
	v_mul_f32_e32 v34, 0x45800000, v0
	v_cndmask_b32_e64 v34, v0, v34, s[44:45]
	v_pk_mul_f32 v[36:37], v[34:35], v[30:31] op_sel_hi:[0,1]
	v_pk_mul_f32 v[32:33], v[34:35], v[32:33] op_sel_hi:[0,1]
	v_cvt_pk_bf16_f32 v30, v36, v37
	v_cvt_pk_bf16_f32 v31, v32, v33
	s_mov_b64 s[4:5], 0
	v_mov_b32_e32 v35, v34
	v_pk_mul_f32 v[36:37], v[34:35], v[26:27]
	v_pk_mul_f32 v[26:27], v[34:35], v[28:29]
	s_mov_b64 s[4:5], -1
	v_cvt_pk_bf16_f32 v32, v36, v37
	v_cvt_pk_bf16_f32 v33, v26, v27
	s_mov_b64 s[4:5], 0
	v_add_u32_e32 v29, s13, v44
	v_or_b32_e32 v0, v29, v124
	s_mov_b64 s[4:5], -1
	v_lshl_add_u64 v[26:27], v[0:1], 1, s[52:53]
	s_mov_b64 s[4:5], 0
	global_store_dwordx4 v[26:27], v[30:33], off
	v_add_u32_e32 v28, 0x4a000, v45
	v_add_u32_e32 v36, v28, v125
	v_pk_mul_f32 v[26:27], v[34:35], v[22:23]
	v_pk_mul_f32 v[24:25], v[34:35], v[24:25]
	s_mov_b64 s[4:5], -1
	v_cvt_pk_bf16_f32 v22, v26, v27
	v_cvt_pk_bf16_f32 v23, v24, v25
	s_mov_b64 s[4:5], 0
	v_pk_mul_f32 v[26:27], v[34:35], v[18:19]
	v_pk_mul_f32 v[18:19], v[34:35], v[20:21]
	s_mov_b64 s[4:5], -1
	v_cvt_pk_bf16_f32 v24, v26, v27
	v_cvt_pk_bf16_f32 v25, v18, v19
	s_mov_b64 s[4:5], -1
	v_lshl_add_u64 v[18:19], v[0:1], 1, s[52:53]
	global_store_dwordx4 v[18:19], v[22:25], off offset:256
	v_fmamk_f32 v0, v153, 0x3a800000, v242
	v_mul_f32_e32 v18, 0x4b800000, v0
	v_cmp_gt_f32_e64 s[44:45], s79, v0
	s_mov_b64 s[4:5], -1
	v_cndmask_b32_e64 v0, v0, v18, s[44:45]
	v_rsq_f32_e32 v0, v0
	s_nop 0
	v_mul_f32_e32 v18, 0x45800000, v0
	v_cndmask_b32_e64 v18, v0, v18, s[44:45]
	v_pk_mul_f32 v[20:21], v[18:19], v[14:15] op_sel_hi:[0,1]
	v_pk_mul_f32 v[16:17], v[18:19], v[16:17] op_sel_hi:[0,1]
	v_cvt_pk_bf16_f32 v14, v20, v21
	v_cvt_pk_bf16_f32 v15, v16, v17
	s_mov_b64 s[4:5], 0
	v_mov_b32_e32 v19, v18
	v_pk_mul_f32 v[20:21], v[18:19], v[10:11]
	v_pk_mul_f32 v[10:11], v[18:19], v[12:13]
	s_mov_b64 s[4:5], -1
	v_cvt_pk_bf16_f32 v16, v20, v21
	v_cvt_pk_bf16_f32 v17, v10, v11
	s_mov_b64 s[4:5], 0
	v_add_u32_e32 v0, s13, v29
	v_or_b32_e32 v0, v0, v124
	s_mov_b64 s[4:5], -1
	v_lshl_add_u64 v[10:11], v[0:1], 1, s[52:53]
	s_mov_b64 s[4:5], 0
	global_store_dwordx4 v[10:11], v[14:17], off
	s_mov_b32 s4, 0x4a000
	v_add3_u32 v12, v28, v125, s4
	v_pk_mul_f32 v[10:11], v[18:19], v[6:7]
	v_pk_mul_f32 v[8:9], v[18:19], v[8:9]
	s_mov_b64 s[4:5], -1
	v_cvt_pk_bf16_f32 v6, v10, v11
	v_cvt_pk_bf16_f32 v7, v8, v9
	s_mov_b64 s[4:5], 0
	v_pk_mul_f32 v[10:11], v[18:19], v[2:3]
	v_pk_mul_f32 v[2:3], v[18:19], v[4:5]
	s_mov_b64 s[4:5], -1
	v_cvt_pk_bf16_f32 v8, v10, v11
	v_cvt_pk_bf16_f32 v9, v2, v3
	s_mov_b64 s[4:5], -1
	v_lshl_add_u64 v[2:3], v[0:1], 1, s[52:53]
	global_store_dwordx4 v[2:3], v[6:9], off offset:256
	s_branch .LBB0_359
